# gMLP LayerNorm stats: the last butterfly hop (consumer inside the lane-0 block) also moved from ds_bpermute to v_permlane32_swap
# baseline (speedup 1.0000x reference)
; #define LAS __attribute__((address_space(3)))
; __device__ __forceinline__ void gmlp_item(const u16* P, const float* lnw, const float* lnb, const float* wsl  , const float* bsl  , u16* Y, int c, int h, LAS unsigned char* L, int tid) {
;     const int lane = tid & 63, w = tid >> 6;
;     const int R0 = c < 64 ? 128 * c : TL + 128 * (c - 64);
;     LAS u16* Wb = (LAS u16*)L; LAS u16* Vb = (LAS u16*)(L + 34816); LAS float* mean = (LAS float*)(L + 69632); LAS float* rstd = mean + 128;
;     float4 wreg[8]; uint4 srow[16], vch[4], uu[4], zz[4];
;     { const float* wg = wsl + (size_t)h * 16384;
; #pragma unroll
;       for (int i = 0; i < 8; ++i) { const int idx = tid + 512 * i; wreg[i] = *(const float4*)(wg + (idx >> 5) * 128 + (idx & 31) * 4); } }
; #pragma unroll
;     for (int rr = 0; rr < 16; ++rr) srow[rr] = *(const uint4*)(P + (size_t)(R0 + 16 * w + rr) * PST + C_AV + lane * 8);
; #pragma unroll
;     for (int i = 0; i < 4; ++i) { const int idx = tid + 512 * i; vch[i] = *(const uint4*)(P + (size_t)(R0 + (idx >> 4)) * PST + C_AV + h * 128 + (idx & 15) * 8); }
.LBB0_348:
	s_and_b64 vcc, exec, s[0:1]
	s_cbranch_vccz .LBB0_339
	s_and_b32 s18, s17, 3
	s_lshl_b32 s0, s18, 16
	v_lshlrev_b32_e32 v2, 2, v140
	s_add_u32 s0, s13, s0
	v_and_b32_e32 v155, 0x7c, v2
	s_addc_u32 s1, s16, 0
	v_lshlrev_b32_e32 v164, 2, v155
	v_and_b32_e32 v2, 0xffffff80, v2
	v_lshl_add_u64 v[0:1], s[0:1], 0, v[164:165]
	v_ashrrev_i32_e32 v3, 31, v2
	v_add_u32_e32 v6, 0x800, v2
	v_lshl_add_u64 v[4:5], v[2:3], 2, v[0:1]
	v_ashrrev_i32_e32 v7, 31, v6
	v_lshl_add_u64 v[6:7], v[6:7], 2, v[0:1]
	global_load_dwordx4 v[76:79], v[4:5], off
	global_load_dwordx4 v[72:75], v[6:7], off
	v_add_u32_e32 v4, 0x1000, v2
	v_ashrrev_i32_e32 v5, 31, v4
	v_add_u32_e32 v6, 0x1800, v2
	v_lshl_add_u64 v[4:5], v[4:5], 2, v[0:1]
	v_ashrrev_i32_e32 v7, 31, v6
	v_lshl_add_u64 v[6:7], v[6:7], 2, v[0:1]
	global_load_dwordx4 v[68:71], v[4:5], off
	global_load_dwordx4 v[64:67], v[6:7], off
	v_add_u32_e32 v4, 0x2000, v2
	v_ashrrev_i32_e32 v5, 31, v4
	v_add_u32_e32 v6, 0x2800, v2
	v_lshl_add_u64 v[4:5], v[4:5], 2, v[0:1]
	v_ashrrev_i32_e32 v7, 31, v6
	v_lshl_add_u64 v[6:7], v[6:7], 2, v[0:1]
	global_load_dwordx4 v[24:27], v[4:5], off
	global_load_dwordx4 v[20:23], v[6:7], off
	v_add_u32_e32 v4, 0x3000, v2
	v_ashrrev_i32_e32 v152, 6, v140
	v_ashrrev_i32_e32 v5, 31, v4
	v_add_u32_e32 v2, 0x3800, v2
	s_lshl_b32 s0, s17, 5
	v_lshl_add_u64 v[4:5], v[4:5], 2, v[0:1]
	v_ashrrev_i32_e32 v3, 31, v2
	s_and_b32 s19, s0, 0xffffff80
	v_lshlrev_b32_e32 v174, 4, v152
	v_lshl_add_u64 v[0:1], v[2:3], 2, v[0:1]
	global_load_dwordx4 v[16:19], v[4:5], off
	global_load_dwordx4 v[12:15], v[0:1], off
	v_and_b32_e32 v166, 63, v140
	v_add_u32_e32 v4, s19, v174
	v_mov_b64_e32 v[32:33], s[78:79]
	v_mad_i64_i32 v[0:1], s[0:1], v4, s93, v[32:33]
	v_lshlrev_b32_e32 v164, 4, v166
	v_or_b32_e32 v2, 1, v4
	v_lshl_add_u64 v[0:1], v[0:1], 0, v[164:165]
	v_mad_i64_i32 v[2:3], s[0:1], v2, s93, v[32:33]
	v_lshl_add_u64 v[2:3], v[2:3], 0, v[164:165]
	global_load_dwordx4 v[36:39], v[0:1], off offset:1024
	global_load_dwordx4 v[136:139], v[2:3], off offset:1024
	v_or_b32_e32 v0, 2, v4
	v_or_b32_e32 v2, 3, v4
	v_mad_i64_i32 v[0:1], s[0:1], v0, s93, v[32:33]
	v_mad_i64_i32 v[2:3], s[0:1], v2, s93, v[32:33]
	v_lshl_add_u64 v[0:1], v[0:1], 0, v[164:165]
	v_lshl_add_u64 v[2:3], v[2:3], 0, v[164:165]
	global_load_dwordx4 v[132:135], v[0:1], off offset:1024
	global_load_dwordx4 v[128:131], v[2:3], off offset:1024
	v_or_b32_e32 v0, 4, v4
	v_or_b32_e32 v2, 5, v4
	v_mad_i64_i32 v[0:1], s[0:1], v0, s93, v[32:33]
	v_mad_i64_i32 v[2:3], s[0:1], v2, s93, v[32:33]
	v_lshl_add_u64 v[0:1], v[0:1], 0, v[164:165]
	v_lshl_add_u64 v[2:3], v[2:3], 0, v[164:165]
	global_load_dwordx4 v[124:127], v[0:1], off offset:1024
	global_load_dwordx4 v[120:123], v[2:3], off offset:1024
	v_or_b32_e32 v0, 6, v4
	v_or_b32_e32 v2, 7, v4
	v_mad_i64_i32 v[0:1], s[0:1], v0, s93, v[32:33]
	v_mad_i64_i32 v[2:3], s[0:1], v2, s93, v[32:33]
	v_lshl_add_u64 v[0:1], v[0:1], 0, v[164:165]
	v_lshl_add_u64 v[2:3], v[2:3], 0, v[164:165]
	global_load_dwordx4 v[116:119], v[0:1], off offset:1024
	global_load_dwordx4 v[112:115], v[2:3], off offset:1024
	v_or_b32_e32 v0, 8, v4
	v_or_b32_e32 v2, 9, v4
	v_mad_i64_i32 v[0:1], s[0:1], v0, s93, v[32:33]
	v_mad_i64_i32 v[2:3], s[0:1], v2, s93, v[32:33]
	v_lshl_add_u64 v[0:1], v[0:1], 0, v[164:165]
	v_lshl_add_u64 v[2:3], v[2:3], 0, v[164:165]
	global_load_dwordx4 v[108:111], v[0:1], off offset:1024
	global_load_dwordx4 v[104:107], v[2:3], off offset:1024
	v_or_b32_e32 v0, 10, v4
	v_or_b32_e32 v2, 11, v4
	v_mad_i64_i32 v[0:1], s[0:1], v0, s93, v[32:33]
	v_mad_i64_i32 v[2:3], s[0:1], v2, s93, v[32:33]
	v_lshl_add_u64 v[0:1], v[0:1], 0, v[164:165]
	v_lshl_add_u64 v[2:3], v[2:3], 0, v[164:165]
	global_load_dwordx4 v[100:103], v[0:1], off offset:1024
	global_load_dwordx4 v[96:99], v[2:3], off offset:1024
	v_or_b32_e32 v0, 12, v4
	v_or_b32_e32 v2, 13, v4
	v_mad_i64_i32 v[0:1], s[0:1], v0, s93, v[32:33]
	v_mad_i64_i32 v[2:3], s[0:1], v2, s93, v[32:33]
	v_lshl_add_u64 v[0:1], v[0:1], 0, v[164:165]
	v_lshl_add_u64 v[2:3], v[2:3], 0, v[164:165]
	global_load_dwordx4 v[92:95], v[0:1], off offset:1024
	global_load_dwordx4 v[88:91], v[2:3], off offset:1024
	v_or_b32_e32 v0, 14, v4
	v_or_b32_e32 v2, 15, v4
	v_mad_i64_i32 v[0:1], s[0:1], v0, s93, v[32:33]
	v_mad_i64_i32 v[2:3], s[0:1], v2, s93, v[32:33]
	v_lshl_add_u64 v[0:1], v[0:1], 0, v[164:165]
	v_lshl_add_u64 v[2:3], v[2:3], 0, v[164:165]
	global_load_dwordx4 v[84:87], v[0:1], off offset:1024
	global_load_dwordx4 v[80:83], v[2:3], off offset:1024
	v_add_u32_e32 v0, s19, v149
	v_add_u32_e32 v2, s19, v148
	v_mad_i64_i32 v[0:1], s[0:1], v0, s93, v[32:33]
	s_lshl_b32 s84, s18, 8
	v_mad_i64_i32 v[2:3], s[0:1], v2, s93, v[32:33]
	v_lshl_add_u64 v[0:1], v[0:1], 0, s[84:85]
	v_lshlrev_b32_e32 v164, 1, v150
	v_lshl_add_u64 v[2:3], v[2:3], 0, s[84:85]
	v_add_u32_e32 v157, 0x400, v140
	v_add_u32_e32 v156, 0x600, v140
	v_lshl_add_u64 v[0:1], v[0:1], 0, v[164:165]
	v_lshl_add_u64 v[2:3], v[2:3], 0, v[164:165]
	v_ashrrev_i32_e32 v154, 4, v157
	s_waitcnt vmcnt(15)
; __device__ __forceinline__ float bflo(unsigned w) { return __uint_as_float(w << 16); }
; __device__ __forceinline__ float bfhi(unsigned w) { return __uint_as_float(w & 0xffff0000u); }
; __device__ __forceinline__ void gmlp_item(const u16* P, const float* lnw, const float* lnb, const float* wsl  , const float* bsl  , u16* Y, int c, int h, LAS unsigned char* L, int tid) {
;     ...
;     for (int rr = 0; rr < 16; ++rr) srow[rr] = *(const uint4*)(P + (size_t)(R0 + 16 * w + rr) * PST + C_AV + lane * 8);
; #pragma unroll
;     for (int i = 0; i < 4; ++i) { const int idx = tid + 512 * i; vch[i] = *(const uint4*)(P + (size_t)(R0 + (idx >> 4)) * PST + C_AV + h * 128 + (idx & 15) * 8); }
;     const int te = tid >> 2, ce = (tid & 3) * 32;
; #pragma unroll
;     for (int i = 0; i < 4; ++i) { uu[i] = *(const uint4*)(P + (size_t)(R0 + te) * PST + C_AU + h * 128 + ce + 8 * i); zz[i] = *(const uint4*)(P + (size_t)(R0 + te) * PST + C_AZ + h * 128 + ce + 8 * i); }
; #pragma unroll
;     for (int rr = 0; rr < 16; ++rr) { const int t = 16 * w + rr; const uint4 wv = srow[rr];
;         float x[8] = {bflo(wv.x), bfhi(wv.x), bflo(wv.y), bfhi(wv.y), bflo(wv.z), bfhi(wv.z), bflo(wv.w), bfhi(wv.w)};
;         float s = 0.f;
; #pragma unroll
;         for (int i = 0; i < 8; ++i) s += x[i];
;         const float mu = wave_sum(s) * (1.f / 512.f); float s2 = 0.f;
; #pragma unroll
;         for (int i = 0; i < 8; ++i) { const float d = x[i] - mu; s2 += d * d; }
;         const float var = wave_sum(s2) * (1.f / 512.f);
;         if (lane == 0) { mean[t] = mu; rstd[t] = rsqrtf(var + EPS); } }
	v_lshlrev_b32_e32 v168, 16, v36
	v_and_b32_e32 v169, 0xffff0000, v36
	v_add_f32_e32 v36, 0, v168
	v_lshlrev_b32_e32 v175, 16, v37
	v_add_f32_e32 v36, v36, v169
	v_and_b32_e32 v181, 0xffff0000, v37
	v_add_f32_e32 v36, v36, v175
	v_lshlrev_b32_e32 v182, 16, v38
	v_add_f32_e32 v36, v36, v181
	v_and_b32_e32 v184, 0xffff0000, v38
	v_add_f32_e32 v36, v36, v182
	v_ashrrev_i32_e32 v153, 4, v156
	v_cmp_lt_i32_e32 vcc, v178, v172
	v_lshlrev_b32_e32 v185, 16, v39
	v_add_f32_e32 v36, v36, v184
	global_load_dwordx4 v[28:31], v[0:1], off offset:1024
	global_load_dwordx4 v[8:11], v[2:3], off offset:1024
	v_add_u32_e32 v0, s19, v154
	v_add_u32_e32 v2, s19, v153
	v_cndmask_b32_e32 v44, v171, v178, vcc
	v_and_b32_e32 v186, 0xffff0000, v39
	v_add_f32_e32 v36, v36, v185
	v_mad_i64_i32 v[0:1], s[0:1], v0, s93, v[32:33]
	v_mad_i64_i32 v[2:3], s[0:1], v2, s93, v[32:33]
	v_lshlrev_b32_e32 v34, 5, v140
	v_add_u32_e32 v142, s19, v144
	v_lshlrev_b32_e32 v158, 2, v44
	v_add_f32_e32 v52, v36, v186
	v_lshl_add_u64 v[0:1], v[0:1], 0, s[84:85]
	v_lshl_add_u64 v[2:3], v[2:3], 0, s[84:85]
	v_and_b32_e32 v141, 0x60, v34
	v_mad_i64_i32 v[32:33], s[0:1], v142, s93, v[32:33]
	v_lshl_add_u64 v[0:1], v[0:1], 0, v[164:165]
	v_lshl_add_u64 v[2:3], v[2:3], 0, v[164:165]
	v_lshl_add_u64 v[32:33], v[32:33], 0, s[84:85]
	v_lshlrev_b32_e32 v164, 1, v141
	v_lshl_add_u64 v[60:61], v[32:33], 0, v[164:165]
	global_load_dwordx4 v[4:7], v[0:1], off offset:1024
	s_nop 0
	global_load_dwordx4 v[0:3], v[2:3], off offset:1024
	s_nop 0
	global_load_dwordx4 v[32:35], v[60:61], off offset:48
	global_load_dwordx4 v[40:43], v[60:61], off offset:32
	global_load_dwordx4 v[48:51], v[60:61], off offset:16
	global_load_dwordx4 v[56:59], v[60:61], off
	v_cmp_lt_i32_e32 vcc, v177, v172
	global_load_dwordx4 v[36:39], v[60:61], off offset:2096
	global_load_dwordx4 v[44:47], v[60:61], off offset:2080
	v_cndmask_b32_e32 v54, v171, v177, vcc
	v_lshlrev_b32_e32 v159, 2, v54
	s_waitcnt lgkmcnt(0)
	s_nop 1
	v_add_f32_dpp v161, v52, v52 quad_perm:[1,0,3,2] row_mask:0xf bank_mask:0xf
	global_load_dwordx4 v[52:55], v[60:61], off offset:2064
	s_nop 0
	global_load_dwordx4 v[60:63], v[60:61], off offset:2048
	v_cmp_lt_i32_e32 vcc, v176, v172
	s_waitcnt lgkmcnt(0)
	s_nop 1
	v_add_f32_dpp v162, v161, v161 quad_perm:[2,3,0,1] row_mask:0xf bank_mask:0xf
	v_cndmask_b32_e32 v160, v171, v176, vcc
	v_lshlrev_b32_e32 v160, 2, v160
	v_xor_b32_e32 v161, 8, v171
	v_cmp_lt_i32_e32 vcc, v161, v172
	s_waitcnt lgkmcnt(0)
	s_nop 1
	v_add_f32_dpp v163, v162, v162 row_half_mirror row_mask:0xf bank_mask:0xf
	v_cndmask_b32_e32 v161, v171, v161, vcc
	v_lshlrev_b32_e32 v161, 2, v161
	v_xor_b32_e32 v162, 16, v171
	v_cmp_lt_i32_e32 vcc, v162, v172
	s_waitcnt lgkmcnt(0)
	s_nop 1
	v_add_f32_dpp v167, v163, v163 row_mirror row_mask:0xf bank_mask:0xf
	v_cndmask_b32_e32 v162, v171, v162, vcc
	v_lshlrev_b32_e32 v162, 2, v162
	v_xor_b32_e32 v163, 32, v171
	v_cmp_lt_i32_e32 vcc, v163, v172
	s_waitcnt lgkmcnt(0)
	v_mov_b32_e32 v187, v167
	s_nop 1
	v_permlane16_swap_b32_e32 v167, v187
	v_add_f32_e32 v167, v167, v187
	v_cndmask_b32_e32 v163, v171, v163, vcc
	v_lshlrev_b32_e32 v163, 2, v163
	v_cmp_eq_u32_e32 vcc, 0, v166
	v_lshl_add_u32 v166, v174, 2, 0
	s_waitcnt lgkmcnt(0)
	v_mov_b32_e32 v187, v167
	s_nop 1
	v_permlane32_swap_b32_e32 v167, v187
	v_add_f32_e32 v167, v167, v187
	v_fmac_f32_e32 v169, 0xbb000000, v167
	v_fmac_f32_e32 v168, 0xbb000000, v167
	v_mul_f32_e32 v169, v169, v169
	v_fmac_f32_e32 v169, v168, v168
	v_fmac_f32_e32 v175, 0xbb000000, v167
	v_fmac_f32_e32 v169, v175, v175
	v_fmac_f32_e32 v181, 0xbb000000, v167
	v_fmac_f32_e32 v169, v181, v181
	v_fmac_f32_e32 v182, 0xbb000000, v167
	v_fmac_f32_e32 v169, v182, v182
	v_fmac_f32_e32 v184, 0xbb000000, v167
	v_fmac_f32_e32 v169, v184, v184
	v_fmac_f32_e32 v185, 0xbb000000, v167
	v_fmac_f32_e32 v169, v185, v185
	v_fmac_f32_e32 v186, 0xbb000000, v167
	v_fmac_f32_e32 v169, v186, v186
	s_waitcnt lgkmcnt(0)
	s_nop 1
	v_add_f32_dpp v168, v169, v169 quad_perm:[1,0,3,2] row_mask:0xf bank_mask:0xf
	s_waitcnt lgkmcnt(0)
	s_nop 1
	v_add_f32_dpp v168, v168, v168 quad_perm:[2,3,0,1] row_mask:0xf bank_mask:0xf
	s_waitcnt lgkmcnt(0)
	s_nop 1
	v_add_f32_dpp v168, v168, v168 row_half_mirror row_mask:0xf bank_mask:0xf
	s_waitcnt lgkmcnt(0)
	s_nop 1
	v_add_f32_dpp v168, v168, v168 row_mirror row_mask:0xf bank_mask:0xf
	s_waitcnt lgkmcnt(0)
	v_mov_b32_e32 v169, v168
	s_nop 1
	v_permlane16_swap_b32_e32 v168, v169
	v_add_f32_e32 v168, v168, v169
	v_mov_b32_e32 v169, v168
	s_nop 1
	v_permlane32_swap_b32_e32 v168, v169
	s_and_saveexec_b64 s[22:23], vcc
	s_cbranch_execz .LBB0_351
	s_waitcnt lgkmcnt(0)
	v_add_f32_e32 v168, v168, v169
	v_fmamk_f32 v168, v168, 0x3b000000, v179
	v_mul_f32_e32 v169, 0x4b800000, v168
	v_cmp_gt_f32_e64 s[0:1], s91, v168
	v_mul_f32_e32 v167, 0x3b000000, v167
	s_nop 0
	v_cndmask_b32_e64 v168, v168, v169, s[0:1]
	v_rsq_f32_e32 v168, v168
	v_add_u32_e32 v169, 0x11000, v166
	ds_write_b32 v169, v167
	v_mul_f32_e32 v167, 0x45800000, v168
	v_cndmask_b32_e64 v167, v168, v167, s[0:1]
	v_add_u32_e32 v168, 0x11200, v166
	ds_write_b32 v168, v167
; __device__ __forceinline__ float bflo(unsigned w) { return __uint_as_float(w << 16); }
; __device__ __forceinline__ float bfhi(unsigned w) { return __uint_as_float(w & 0xffff0000u); }
; __device__ __forceinline__ float wave_sum(float v) {
; #pragma unroll
;     for (int o = 1; o < 64; o <<= 1) v += __shfl_xor(v, o);
;     return v;
; }
; __device__ __forceinline__ void gmlp_item(const u16* P, const float* lnw, const float* lnb, const float* wsl  , const float* bsl  , u16* Y, int c, int h, LAS unsigned char* L, int tid) {
;     ...
;     for (int rr = 0; rr < 16; ++rr) { const int t = 16 * w + rr; const uint4 wv = srow[rr];
;         float x[8] = {bflo(wv.x), bfhi(wv.x), bflo(wv.y), bfhi(wv.y), bflo(wv.z), bfhi(wv.z), bflo(wv.w), bfhi(wv.w)};
;         float s = 0.f;
; #pragma unroll
;         for (int i = 0; i < 8; ++i) s += x[i];
;         const float mu = wave_sum(s) * (1.f / 512.f); float s2 = 0.f;
; #pragma unroll
;         for (int i = 0; i < 8; ++i) { const float d = x[i] - mu; s2 += d * d; }
;         const float var = wave_sum(s2) * (1.f / 512.f);
;         if (lane == 0) { mean[t] = mu; rstd[t] = rsqrtf(var + EPS); } }
.LBB0_351:
	s_or_b64 exec, exec, s[22:23]
	s_waitcnt vmcnt(26)
	v_lshlrev_b32_e32 v167, 16, v136
	v_and_b32_e32 v168, 0xffff0000, v136
	v_add_f32_e32 v136, 0, v167
	s_waitcnt lgkmcnt(0)
	v_lshlrev_b32_e32 v169, 16, v137
	v_add_f32_e32 v136, v136, v168
	v_and_b32_e32 v137, 0xffff0000, v137
	v_add_f32_e32 v136, v136, v169
	v_lshlrev_b32_e32 v174, 16, v138
	v_add_f32_e32 v136, v136, v137
	v_and_b32_e32 v138, 0xffff0000, v138
	v_add_f32_e32 v136, v136, v174
	v_lshlrev_b32_e32 v175, 16, v139
	v_add_f32_e32 v136, v136, v138
	v_and_b32_e32 v139, 0xffff0000, v139
	v_add_f32_e32 v136, v136, v175
	v_add_f32_e32 v136, v136, v139
	s_waitcnt lgkmcnt(0)
	s_nop 1
	v_add_f32_dpp v136, v136, v136 quad_perm:[1,0,3,2] row_mask:0xf bank_mask:0xf
	s_waitcnt lgkmcnt(0)
	s_nop 1
	v_add_f32_dpp v136, v136, v136 quad_perm:[2,3,0,1] row_mask:0xf bank_mask:0xf
	s_waitcnt lgkmcnt(0)
	s_nop 1
	v_add_f32_dpp v136, v136, v136 row_half_mirror row_mask:0xf bank_mask:0xf
	s_waitcnt lgkmcnt(0)
	s_nop 1
	v_add_f32_dpp v136, v136, v136 row_mirror row_mask:0xf bank_mask:0xf
	s_waitcnt lgkmcnt(0)
	v_mov_b32_e32 v181, v136
	s_nop 1
	v_permlane16_swap_b32_e32 v136, v181
	v_add_f32_e32 v136, v136, v181
	s_waitcnt lgkmcnt(0)
	v_mov_b32_e32 v181, v136
	s_nop 1
	v_permlane32_swap_b32_e32 v136, v181
	v_add_f32_e32 v136, v136, v181
	v_fmac_f32_e32 v168, 0xbb000000, v136
	v_fmac_f32_e32 v167, 0xbb000000, v136
	v_mul_f32_e32 v168, v168, v168
	v_fmac_f32_e32 v169, 0xbb000000, v136
	v_fmac_f32_e32 v168, v167, v167
	v_fmac_f32_e32 v137, 0xbb000000, v136
	v_fmac_f32_e32 v168, v169, v169
	v_fmac_f32_e32 v174, 0xbb000000, v136
	v_fmac_f32_e32 v168, v137, v137
	v_fmac_f32_e32 v138, 0xbb000000, v136
	v_fmac_f32_e32 v168, v174, v174
	v_fmac_f32_e32 v175, 0xbb000000, v136
	v_fmac_f32_e32 v168, v138, v138
	v_fmac_f32_e32 v168, v175, v175
	v_fmac_f32_e32 v139, 0xbb000000, v136
	v_fmac_f32_e32 v168, v139, v139
	s_waitcnt lgkmcnt(0)
	s_nop 1
	v_add_f32_dpp v137, v168, v168 quad_perm:[1,0,3,2] row_mask:0xf bank_mask:0xf
	s_waitcnt lgkmcnt(0)
	s_nop 1
	v_add_f32_dpp v137, v137, v137 quad_perm:[2,3,0,1] row_mask:0xf bank_mask:0xf
	s_waitcnt lgkmcnt(0)
	s_nop 1
	v_add_f32_dpp v137, v137, v137 row_half_mirror row_mask:0xf bank_mask:0xf
	s_waitcnt lgkmcnt(0)
	s_nop 1
	v_add_f32_dpp v137, v137, v137 row_mirror row_mask:0xf bank_mask:0xf
	s_waitcnt lgkmcnt(0)
	v_mov_b32_e32 v138, v137
	s_nop 1
	v_permlane16_swap_b32_e32 v137, v138
	v_add_f32_e32 v137, v137, v138
	v_mov_b32_e32 v138, v137
	s_nop 1
	v_permlane32_swap_b32_e32 v137, v138
	s_and_saveexec_b64 s[22:23], vcc
	s_cbranch_execz .LBB0_353
	s_waitcnt lgkmcnt(0)
	v_add_f32_e32 v137, v137, v138
	v_fmamk_f32 v137, v137, 0x3b000000, v179
	v_mul_f32_e32 v138, 0x4b800000, v137
	v_cmp_gt_f32_e64 s[0:1], s91, v137
	v_mul_f32_e32 v136, 0x3b000000, v136
	s_nop 0
	v_cndmask_b32_e64 v137, v137, v138, s[0:1]
	v_rsq_f32_e32 v137, v137
	v_add_u32_e32 v138, 0x11004, v166
	ds_write_b32 v138, v136
	v_mul_f32_e32 v136, 0x45800000, v137
	v_cndmask_b32_e64 v136, v137, v136, s[0:1]
	v_add_u32_e32 v137, 0x11204, v166
	ds_write_b32 v137, v136
.LBB0_353:
	s_or_b64 exec, exec, s[22:23]
	s_waitcnt vmcnt(25)
	v_lshlrev_b32_e32 v136, 16, v132
	v_and_b32_e32 v137, 0xffff0000, v132
	v_add_f32_e32 v132, 0, v136
	s_waitcnt lgkmcnt(0)
	v_lshlrev_b32_e32 v138, 16, v133
	v_add_f32_e32 v132, v132, v137
	v_and_b32_e32 v133, 0xffff0000, v133
	v_add_f32_e32 v132, v132, v138
	v_lshlrev_b32_e32 v139, 16, v134
	v_add_f32_e32 v132, v132, v133
	v_and_b32_e32 v134, 0xffff0000, v134
	v_add_f32_e32 v132, v132, v139
	v_lshlrev_b32_e32 v167, 16, v135
	v_add_f32_e32 v132, v132, v134
	v_and_b32_e32 v135, 0xffff0000, v135
	v_add_f32_e32 v132, v132, v167
	v_add_f32_e32 v132, v132, v135
	s_waitcnt lgkmcnt(0)
	s_nop 1
	v_add_f32_dpp v132, v132, v132 quad_perm:[1,0,3,2] row_mask:0xf bank_mask:0xf
	s_waitcnt lgkmcnt(0)
	s_nop 1
	v_add_f32_dpp v132, v132, v132 quad_perm:[2,3,0,1] row_mask:0xf bank_mask:0xf
	s_waitcnt lgkmcnt(0)
	s_nop 1
	v_add_f32_dpp v132, v132, v132 row_half_mirror row_mask:0xf bank_mask:0xf
	s_waitcnt lgkmcnt(0)
	s_nop 1
	v_add_f32_dpp v132, v132, v132 row_mirror row_mask:0xf bank_mask:0xf
	s_waitcnt lgkmcnt(0)
	v_mov_b32_e32 v168, v132
	s_nop 1
	v_permlane16_swap_b32_e32 v132, v168
	v_add_f32_e32 v132, v132, v168
	s_waitcnt lgkmcnt(0)
	v_mov_b32_e32 v168, v132
	s_nop 1
	v_permlane32_swap_b32_e32 v132, v168
	v_add_f32_e32 v132, v132, v168
	v_fmac_f32_e32 v137, 0xbb000000, v132
	v_fmac_f32_e32 v136, 0xbb000000, v132
	v_mul_f32_e32 v137, v137, v137
	v_fmac_f32_e32 v138, 0xbb000000, v132
	v_fmac_f32_e32 v137, v136, v136
	v_fmac_f32_e32 v133, 0xbb000000, v132
	v_fmac_f32_e32 v137, v138, v138
	v_fmac_f32_e32 v139, 0xbb000000, v132
	v_fmac_f32_e32 v137, v133, v133
	v_fmac_f32_e32 v134, 0xbb000000, v132
	v_fmac_f32_e32 v137, v139, v139
	v_fmac_f32_e32 v167, 0xbb000000, v132
	v_fmac_f32_e32 v137, v134, v134
	v_fmac_f32_e32 v137, v167, v167
	v_fmac_f32_e32 v135, 0xbb000000, v132
	v_fmac_f32_e32 v137, v135, v135
	s_waitcnt lgkmcnt(0)
	s_nop 1
	v_add_f32_dpp v133, v137, v137 quad_perm:[1,0,3,2] row_mask:0xf bank_mask:0xf
	s_waitcnt lgkmcnt(0)
	s_nop 1
	v_add_f32_dpp v133, v133, v133 quad_perm:[2,3,0,1] row_mask:0xf bank_mask:0xf
	s_waitcnt lgkmcnt(0)
	s_nop 1
	v_add_f32_dpp v133, v133, v133 row_half_mirror row_mask:0xf bank_mask:0xf
	s_waitcnt lgkmcnt(0)
	s_nop 1
	v_add_f32_dpp v133, v133, v133 row_mirror row_mask:0xf bank_mask:0xf
	s_waitcnt lgkmcnt(0)
	v_mov_b32_e32 v134, v133
	s_nop 1
	v_permlane16_swap_b32_e32 v133, v134
	v_add_f32_e32 v133, v133, v134
	v_mov_b32_e32 v134, v133
	s_nop 1
	v_permlane32_swap_b32_e32 v133, v134
	s_and_saveexec_b64 s[22:23], vcc
	s_cbranch_execz .LBB0_355
	s_waitcnt lgkmcnt(0)
	v_add_f32_e32 v133, v133, v134
	v_fmamk_f32 v133, v133, 0x3b000000, v179
	v_mul_f32_e32 v134, 0x4b800000, v133
	v_cmp_gt_f32_e64 s[0:1], s91, v133
	v_mul_f32_e32 v132, 0x3b000000, v132
	s_nop 0
	v_cndmask_b32_e64 v133, v133, v134, s[0:1]
	v_rsq_f32_e32 v133, v133
	v_add_u32_e32 v134, 0x11008, v166
	ds_write_b32 v134, v132
	v_mul_f32_e32 v132, 0x45800000, v133
	v_cndmask_b32_e64 v132, v133, v132, s[0:1]
	v_add_u32_e32 v133, 0x11208, v166
	ds_write_b32 v133, v132
; __device__ __forceinline__ float bflo(unsigned w) { return __uint_as_float(w << 16); }
; __device__ __forceinline__ float bfhi(unsigned w) { return __uint_as_float(w & 0xffff0000u); }
; __device__ __forceinline__ float wave_sum(float v) {
; #pragma unroll
;     for (int o = 1; o < 64; o <<= 1) v += __shfl_xor(v, o);
;     return v;
; }
; __device__ __forceinline__ void gmlp_item(const u16* P, const float* lnw, const float* lnb, const float* wsl  , const float* bsl  , u16* Y, int c, int h, LAS unsigned char* L, int tid) {
;     ...
;     for (int rr = 0; rr < 16; ++rr) { const int t = 16 * w + rr; const uint4 wv = srow[rr];
;         float x[8] = {bflo(wv.x), bfhi(wv.x), bflo(wv.y), bfhi(wv.y), bflo(wv.z), bfhi(wv.z), bflo(wv.w), bfhi(wv.w)};
;         float s = 0.f;
; #pragma unroll
;         for (int i = 0; i < 8; ++i) s += x[i];
;         const float mu = wave_sum(s) * (1.f / 512.f); float s2 = 0.f;
; #pragma unroll
;         for (int i = 0; i < 8; ++i) { const float d = x[i] - mu; s2 += d * d; }
;         const float var = wave_sum(s2) * (1.f / 512.f);
;         if (lane == 0) { mean[t] = mu; rstd[t] = rsqrtf(var + EPS); } }
.LBB0_355:
	s_or_b64 exec, exec, s[22:23]
	s_waitcnt vmcnt(24)
	v_lshlrev_b32_e32 v132, 16, v128
	v_and_b32_e32 v133, 0xffff0000, v128
	v_add_f32_e32 v128, 0, v132
	s_waitcnt lgkmcnt(0)
	v_lshlrev_b32_e32 v134, 16, v129
	v_add_f32_e32 v128, v128, v133
	v_and_b32_e32 v129, 0xffff0000, v129
	v_add_f32_e32 v128, v128, v134
	v_lshlrev_b32_e32 v135, 16, v130
	v_add_f32_e32 v128, v128, v129
	v_and_b32_e32 v130, 0xffff0000, v130
	v_add_f32_e32 v128, v128, v135
	v_lshlrev_b32_e32 v136, 16, v131
	v_add_f32_e32 v128, v128, v130
	v_and_b32_e32 v131, 0xffff0000, v131
	v_add_f32_e32 v128, v128, v136
	v_add_f32_e32 v128, v128, v131
	s_waitcnt lgkmcnt(0)
	s_nop 1
	v_add_f32_dpp v128, v128, v128 quad_perm:[1,0,3,2] row_mask:0xf bank_mask:0xf
	s_waitcnt lgkmcnt(0)
	s_nop 1
	v_add_f32_dpp v128, v128, v128 quad_perm:[2,3,0,1] row_mask:0xf bank_mask:0xf
	s_waitcnt lgkmcnt(0)
	s_nop 1
	v_add_f32_dpp v128, v128, v128 row_half_mirror row_mask:0xf bank_mask:0xf
	s_waitcnt lgkmcnt(0)
	s_nop 1
	v_add_f32_dpp v128, v128, v128 row_mirror row_mask:0xf bank_mask:0xf
	s_waitcnt lgkmcnt(0)
	v_mov_b32_e32 v137, v128
	s_nop 1
	v_permlane16_swap_b32_e32 v128, v137
	v_add_f32_e32 v128, v128, v137
	s_waitcnt lgkmcnt(0)
	v_mov_b32_e32 v137, v128
	s_nop 1
	v_permlane32_swap_b32_e32 v128, v137
	v_add_f32_e32 v128, v128, v137
	v_fmac_f32_e32 v133, 0xbb000000, v128
	v_fmac_f32_e32 v132, 0xbb000000, v128
	v_mul_f32_e32 v133, v133, v133
	v_fmac_f32_e32 v134, 0xbb000000, v128
	v_fmac_f32_e32 v133, v132, v132
	v_fmac_f32_e32 v129, 0xbb000000, v128
	v_fmac_f32_e32 v133, v134, v134
	v_fmac_f32_e32 v135, 0xbb000000, v128
	v_fmac_f32_e32 v133, v129, v129
	v_fmac_f32_e32 v130, 0xbb000000, v128
	v_fmac_f32_e32 v133, v135, v135
	v_fmac_f32_e32 v136, 0xbb000000, v128
	v_fmac_f32_e32 v133, v130, v130
	v_fmac_f32_e32 v133, v136, v136
	v_fmac_f32_e32 v131, 0xbb000000, v128
	v_fmac_f32_e32 v133, v131, v131
	s_waitcnt lgkmcnt(0)
	s_nop 1
	v_add_f32_dpp v129, v133, v133 quad_perm:[1,0,3,2] row_mask:0xf bank_mask:0xf
	s_waitcnt lgkmcnt(0)
	s_nop 1
	v_add_f32_dpp v129, v129, v129 quad_perm:[2,3,0,1] row_mask:0xf bank_mask:0xf
	s_waitcnt lgkmcnt(0)
	s_nop 1
	v_add_f32_dpp v129, v129, v129 row_half_mirror row_mask:0xf bank_mask:0xf
	s_waitcnt lgkmcnt(0)
	s_nop 1
	v_add_f32_dpp v129, v129, v129 row_mirror row_mask:0xf bank_mask:0xf
	s_waitcnt lgkmcnt(0)
	v_mov_b32_e32 v130, v129
	s_nop 1
	v_permlane16_swap_b32_e32 v129, v130
	v_add_f32_e32 v129, v129, v130
	v_mov_b32_e32 v130, v129
	s_nop 1
	v_permlane32_swap_b32_e32 v129, v130
	s_and_saveexec_b64 s[22:23], vcc
	s_cbranch_execz .LBB0_357
	s_waitcnt lgkmcnt(0)
	v_add_f32_e32 v129, v129, v130
	v_fmamk_f32 v129, v129, 0x3b000000, v179
	v_mul_f32_e32 v130, 0x4b800000, v129
	v_cmp_gt_f32_e64 s[0:1], s91, v129
	v_mul_f32_e32 v128, 0x3b000000, v128
	s_nop 0
	v_cndmask_b32_e64 v129, v129, v130, s[0:1]
	v_rsq_f32_e32 v129, v129
	v_add_u32_e32 v130, 0x1100c, v166
	ds_write_b32 v130, v128
	v_mul_f32_e32 v128, 0x45800000, v129
	v_cndmask_b32_e64 v128, v129, v128, s[0:1]
	v_add_u32_e32 v129, 0x1120c, v166
	ds_write_b32 v129, v128
.LBB0_357:
	s_or_b64 exec, exec, s[22:23]
	s_waitcnt vmcnt(23)
	v_lshlrev_b32_e32 v128, 16, v124
	v_and_b32_e32 v129, 0xffff0000, v124
	v_add_f32_e32 v124, 0, v128
	s_waitcnt lgkmcnt(0)
	v_lshlrev_b32_e32 v130, 16, v125
	v_add_f32_e32 v124, v124, v129
	v_and_b32_e32 v125, 0xffff0000, v125
	v_add_f32_e32 v124, v124, v130
	v_lshlrev_b32_e32 v131, 16, v126
	v_add_f32_e32 v124, v124, v125
	v_and_b32_e32 v126, 0xffff0000, v126
	v_add_f32_e32 v124, v124, v131
	v_lshlrev_b32_e32 v132, 16, v127
	v_add_f32_e32 v124, v124, v126
	v_and_b32_e32 v127, 0xffff0000, v127
	v_add_f32_e32 v124, v124, v132
	v_add_f32_e32 v124, v124, v127
	s_waitcnt lgkmcnt(0)
	s_nop 1
	v_add_f32_dpp v124, v124, v124 quad_perm:[1,0,3,2] row_mask:0xf bank_mask:0xf
	s_waitcnt lgkmcnt(0)
	s_nop 1
	v_add_f32_dpp v124, v124, v124 quad_perm:[2,3,0,1] row_mask:0xf bank_mask:0xf
	s_waitcnt lgkmcnt(0)
	s_nop 1
	v_add_f32_dpp v124, v124, v124 row_half_mirror row_mask:0xf bank_mask:0xf
	s_waitcnt lgkmcnt(0)
	s_nop 1
	v_add_f32_dpp v124, v124, v124 row_mirror row_mask:0xf bank_mask:0xf
	s_waitcnt lgkmcnt(0)
	v_mov_b32_e32 v133, v124
	s_nop 1
	v_permlane16_swap_b32_e32 v124, v133
	v_add_f32_e32 v124, v124, v133
	s_waitcnt lgkmcnt(0)
	v_mov_b32_e32 v133, v124
	s_nop 1
	v_permlane32_swap_b32_e32 v124, v133
	v_add_f32_e32 v124, v124, v133
	v_fmac_f32_e32 v129, 0xbb000000, v124
	v_fmac_f32_e32 v128, 0xbb000000, v124
	v_mul_f32_e32 v129, v129, v129
	v_fmac_f32_e32 v130, 0xbb000000, v124
	v_fmac_f32_e32 v129, v128, v128
	v_fmac_f32_e32 v125, 0xbb000000, v124
	v_fmac_f32_e32 v129, v130, v130
	v_fmac_f32_e32 v131, 0xbb000000, v124
	v_fmac_f32_e32 v129, v125, v125
	v_fmac_f32_e32 v126, 0xbb000000, v124
	v_fmac_f32_e32 v129, v131, v131
	v_fmac_f32_e32 v132, 0xbb000000, v124
	v_fmac_f32_e32 v129, v126, v126
	v_fmac_f32_e32 v129, v132, v132
	v_fmac_f32_e32 v127, 0xbb000000, v124
	v_fmac_f32_e32 v129, v127, v127
	s_waitcnt lgkmcnt(0)
	s_nop 1
	v_add_f32_dpp v125, v129, v129 quad_perm:[1,0,3,2] row_mask:0xf bank_mask:0xf
	s_waitcnt lgkmcnt(0)
	s_nop 1
	v_add_f32_dpp v125, v125, v125 quad_perm:[2,3,0,1] row_mask:0xf bank_mask:0xf
	s_waitcnt lgkmcnt(0)
	s_nop 1
	v_add_f32_dpp v125, v125, v125 row_half_mirror row_mask:0xf bank_mask:0xf
	s_waitcnt lgkmcnt(0)
	s_nop 1
	v_add_f32_dpp v125, v125, v125 row_mirror row_mask:0xf bank_mask:0xf
	s_waitcnt lgkmcnt(0)
	v_mov_b32_e32 v126, v125
	s_nop 1
	v_permlane16_swap_b32_e32 v125, v126
	v_add_f32_e32 v125, v125, v126
	v_mov_b32_e32 v126, v125
	s_nop 1
	v_permlane32_swap_b32_e32 v125, v126
	s_and_saveexec_b64 s[22:23], vcc
	s_cbranch_execz .LBB0_359
	s_waitcnt lgkmcnt(0)
	v_add_f32_e32 v125, v125, v126
	v_fmamk_f32 v125, v125, 0x3b000000, v179
	v_mul_f32_e32 v126, 0x4b800000, v125
	v_cmp_gt_f32_e64 s[0:1], s91, v125
	v_mul_f32_e32 v124, 0x3b000000, v124
	s_nop 0
	v_cndmask_b32_e64 v125, v125, v126, s[0:1]
	v_rsq_f32_e32 v125, v125
	v_add_u32_e32 v126, 0x11010, v166
	ds_write_b32 v126, v124
	v_mul_f32_e32 v124, 0x45800000, v125
	v_cndmask_b32_e64 v124, v125, v124, s[0:1]
	v_add_u32_e32 v125, 0x11210, v166
	ds_write_b32 v125, v124
; __device__ __forceinline__ float bflo(unsigned w) { return __uint_as_float(w << 16); }
; __device__ __forceinline__ float bfhi(unsigned w) { return __uint_as_float(w & 0xffff0000u); }
; __device__ __forceinline__ float wave_sum(float v) {
; #pragma unroll
;     for (int o = 1; o < 64; o <<= 1) v += __shfl_xor(v, o);
;     return v;
; }
; __device__ __forceinline__ void gmlp_item(const u16* P, const float* lnw, const float* lnb, const float* wsl  , const float* bsl  , u16* Y, int c, int h, LAS unsigned char* L, int tid) {
;     ...
;     for (int rr = 0; rr < 16; ++rr) { const int t = 16 * w + rr; const uint4 wv = srow[rr];
;         float x[8] = {bflo(wv.x), bfhi(wv.x), bflo(wv.y), bfhi(wv.y), bflo(wv.z), bfhi(wv.z), bflo(wv.w), bfhi(wv.w)};
;         float s = 0.f;
; #pragma unroll
;         for (int i = 0; i < 8; ++i) s += x[i];
;         const float mu = wave_sum(s) * (1.f / 512.f); float s2 = 0.f;
; #pragma unroll
;         for (int i = 0; i < 8; ++i) { const float d = x[i] - mu; s2 += d * d; }
;         const float var = wave_sum(s2) * (1.f / 512.f);
;         if (lane == 0) { mean[t] = mu; rstd[t] = rsqrtf(var + EPS); } }
.LBB0_359:
	s_or_b64 exec, exec, s[22:23]
	s_waitcnt vmcnt(22)
	v_lshlrev_b32_e32 v124, 16, v120
	v_and_b32_e32 v125, 0xffff0000, v120
	v_add_f32_e32 v120, 0, v124
	s_waitcnt lgkmcnt(0)
	v_lshlrev_b32_e32 v126, 16, v121
	v_add_f32_e32 v120, v120, v125
	v_and_b32_e32 v121, 0xffff0000, v121
	v_add_f32_e32 v120, v120, v126
	v_lshlrev_b32_e32 v127, 16, v122
	v_add_f32_e32 v120, v120, v121
	v_and_b32_e32 v122, 0xffff0000, v122
	v_add_f32_e32 v120, v120, v127
	v_lshlrev_b32_e32 v128, 16, v123
	v_add_f32_e32 v120, v120, v122
	v_and_b32_e32 v123, 0xffff0000, v123
	v_add_f32_e32 v120, v120, v128
	v_add_f32_e32 v120, v120, v123
	s_waitcnt lgkmcnt(0)
	s_nop 1
	v_add_f32_dpp v120, v120, v120 quad_perm:[1,0,3,2] row_mask:0xf bank_mask:0xf
	s_waitcnt lgkmcnt(0)
	s_nop 1
	v_add_f32_dpp v120, v120, v120 quad_perm:[2,3,0,1] row_mask:0xf bank_mask:0xf
	s_waitcnt lgkmcnt(0)
	s_nop 1
	v_add_f32_dpp v120, v120, v120 row_half_mirror row_mask:0xf bank_mask:0xf
	s_waitcnt lgkmcnt(0)
	s_nop 1
	v_add_f32_dpp v120, v120, v120 row_mirror row_mask:0xf bank_mask:0xf
	s_waitcnt lgkmcnt(0)
	v_mov_b32_e32 v129, v120
	s_nop 1
	v_permlane16_swap_b32_e32 v120, v129
	v_add_f32_e32 v120, v120, v129
	s_waitcnt lgkmcnt(0)
	v_mov_b32_e32 v129, v120
	s_nop 1
	v_permlane32_swap_b32_e32 v120, v129
	v_add_f32_e32 v120, v120, v129
	v_fmac_f32_e32 v125, 0xbb000000, v120
	v_fmac_f32_e32 v124, 0xbb000000, v120
	v_mul_f32_e32 v125, v125, v125
	v_fmac_f32_e32 v126, 0xbb000000, v120
	v_fmac_f32_e32 v125, v124, v124
	v_fmac_f32_e32 v121, 0xbb000000, v120
	v_fmac_f32_e32 v125, v126, v126
	v_fmac_f32_e32 v127, 0xbb000000, v120
	v_fmac_f32_e32 v125, v121, v121
	v_fmac_f32_e32 v122, 0xbb000000, v120
	v_fmac_f32_e32 v125, v127, v127
	v_fmac_f32_e32 v128, 0xbb000000, v120
	v_fmac_f32_e32 v125, v122, v122
	v_fmac_f32_e32 v125, v128, v128
	v_fmac_f32_e32 v123, 0xbb000000, v120
	v_fmac_f32_e32 v125, v123, v123
	s_waitcnt lgkmcnt(0)
	s_nop 1
	v_add_f32_dpp v121, v125, v125 quad_perm:[1,0,3,2] row_mask:0xf bank_mask:0xf
	s_waitcnt lgkmcnt(0)
	s_nop 1
	v_add_f32_dpp v121, v121, v121 quad_perm:[2,3,0,1] row_mask:0xf bank_mask:0xf
	s_waitcnt lgkmcnt(0)
	s_nop 1
	v_add_f32_dpp v121, v121, v121 row_half_mirror row_mask:0xf bank_mask:0xf
	s_waitcnt lgkmcnt(0)
	s_nop 1
	v_add_f32_dpp v121, v121, v121 row_mirror row_mask:0xf bank_mask:0xf
	s_waitcnt lgkmcnt(0)
	v_mov_b32_e32 v122, v121
	s_nop 1
	v_permlane16_swap_b32_e32 v121, v122
	v_add_f32_e32 v121, v121, v122
	v_mov_b32_e32 v122, v121
	s_nop 1
	v_permlane32_swap_b32_e32 v121, v122
	s_and_saveexec_b64 s[22:23], vcc
	s_cbranch_execz .LBB0_361
	s_waitcnt lgkmcnt(0)
	v_add_f32_e32 v121, v121, v122
	v_fmamk_f32 v121, v121, 0x3b000000, v179
	v_mul_f32_e32 v122, 0x4b800000, v121
	v_cmp_gt_f32_e64 s[0:1], s91, v121
	v_mul_f32_e32 v120, 0x3b000000, v120
	s_nop 0
	v_cndmask_b32_e64 v121, v121, v122, s[0:1]
	v_rsq_f32_e32 v121, v121
	v_add_u32_e32 v122, 0x11014, v166
	ds_write_b32 v122, v120
	v_mul_f32_e32 v120, 0x45800000, v121
	v_cndmask_b32_e64 v120, v121, v120, s[0:1]
	v_add_u32_e32 v121, 0x11214, v166
	ds_write_b32 v121, v120
.LBB0_361:
	s_or_b64 exec, exec, s[22:23]
	s_waitcnt vmcnt(21)
	v_lshlrev_b32_e32 v120, 16, v116
	v_and_b32_e32 v121, 0xffff0000, v116
	v_add_f32_e32 v116, 0, v120
	s_waitcnt lgkmcnt(0)
	v_lshlrev_b32_e32 v122, 16, v117
	v_add_f32_e32 v116, v116, v121
	v_and_b32_e32 v117, 0xffff0000, v117
	v_add_f32_e32 v116, v116, v122
	v_lshlrev_b32_e32 v123, 16, v118
	v_add_f32_e32 v116, v116, v117
	v_and_b32_e32 v118, 0xffff0000, v118
	v_add_f32_e32 v116, v116, v123
	v_lshlrev_b32_e32 v124, 16, v119
	v_add_f32_e32 v116, v116, v118
	v_and_b32_e32 v119, 0xffff0000, v119
	v_add_f32_e32 v116, v116, v124
	v_add_f32_e32 v116, v116, v119
	s_waitcnt lgkmcnt(0)
	s_nop 1
	v_add_f32_dpp v116, v116, v116 quad_perm:[1,0,3,2] row_mask:0xf bank_mask:0xf
	s_waitcnt lgkmcnt(0)
	s_nop 1
	v_add_f32_dpp v116, v116, v116 quad_perm:[2,3,0,1] row_mask:0xf bank_mask:0xf
	s_waitcnt lgkmcnt(0)
	s_nop 1
	v_add_f32_dpp v116, v116, v116 row_half_mirror row_mask:0xf bank_mask:0xf
	s_waitcnt lgkmcnt(0)
	s_nop 1
	v_add_f32_dpp v116, v116, v116 row_mirror row_mask:0xf bank_mask:0xf
	s_waitcnt lgkmcnt(0)
	v_mov_b32_e32 v125, v116
	s_nop 1
	v_permlane16_swap_b32_e32 v116, v125
	v_add_f32_e32 v116, v116, v125
	s_waitcnt lgkmcnt(0)
	v_mov_b32_e32 v125, v116
	s_nop 1
	v_permlane32_swap_b32_e32 v116, v125
	v_add_f32_e32 v116, v116, v125
	v_fmac_f32_e32 v121, 0xbb000000, v116
	v_fmac_f32_e32 v120, 0xbb000000, v116
	v_mul_f32_e32 v121, v121, v121
	v_fmac_f32_e32 v122, 0xbb000000, v116
	v_fmac_f32_e32 v121, v120, v120
	v_fmac_f32_e32 v117, 0xbb000000, v116
	v_fmac_f32_e32 v121, v122, v122
	v_fmac_f32_e32 v123, 0xbb000000, v116
	v_fmac_f32_e32 v121, v117, v117
	v_fmac_f32_e32 v118, 0xbb000000, v116
	v_fmac_f32_e32 v121, v123, v123
	v_fmac_f32_e32 v124, 0xbb000000, v116
	v_fmac_f32_e32 v121, v118, v118
	v_fmac_f32_e32 v121, v124, v124
	v_fmac_f32_e32 v119, 0xbb000000, v116
	v_fmac_f32_e32 v121, v119, v119
	s_waitcnt lgkmcnt(0)
	s_nop 1
	v_add_f32_dpp v117, v121, v121 quad_perm:[1,0,3,2] row_mask:0xf bank_mask:0xf
	s_waitcnt lgkmcnt(0)
	s_nop 1
	v_add_f32_dpp v117, v117, v117 quad_perm:[2,3,0,1] row_mask:0xf bank_mask:0xf
	s_waitcnt lgkmcnt(0)
	s_nop 1
	v_add_f32_dpp v117, v117, v117 row_half_mirror row_mask:0xf bank_mask:0xf
	s_waitcnt lgkmcnt(0)
	s_nop 1
	v_add_f32_dpp v117, v117, v117 row_mirror row_mask:0xf bank_mask:0xf
	s_waitcnt lgkmcnt(0)
	v_mov_b32_e32 v118, v117
	s_nop 1
	v_permlane16_swap_b32_e32 v117, v118
	v_add_f32_e32 v117, v117, v118
	v_mov_b32_e32 v118, v117
	s_nop 1
	v_permlane32_swap_b32_e32 v117, v118
	s_and_saveexec_b64 s[22:23], vcc
	s_cbranch_execz .LBB0_363
	s_waitcnt lgkmcnt(0)
	v_add_f32_e32 v117, v117, v118
	v_fmamk_f32 v117, v117, 0x3b000000, v179
	v_mul_f32_e32 v118, 0x4b800000, v117
	v_cmp_gt_f32_e64 s[0:1], s91, v117
	v_mul_f32_e32 v116, 0x3b000000, v116
	s_nop 0
	v_cndmask_b32_e64 v117, v117, v118, s[0:1]
	v_rsq_f32_e32 v117, v117
	v_add_u32_e32 v118, 0x11018, v166
	ds_write_b32 v118, v116
	v_mul_f32_e32 v116, 0x45800000, v117
	v_cndmask_b32_e64 v116, v117, v116, s[0:1]
	v_add_u32_e32 v117, 0x11218, v166
	ds_write_b32 v117, v116
; __device__ __forceinline__ float bflo(unsigned w) { return __uint_as_float(w << 16); }
; __device__ __forceinline__ float bfhi(unsigned w) { return __uint_as_float(w & 0xffff0000u); }
; __device__ __forceinline__ float wave_sum(float v) {
; #pragma unroll
;     for (int o = 1; o < 64; o <<= 1) v += __shfl_xor(v, o);
;     return v;
; }
; __device__ __forceinline__ void gmlp_item(const u16* P, const float* lnw, const float* lnb, const float* wsl  , const float* bsl  , u16* Y, int c, int h, LAS unsigned char* L, int tid) {
;     ...
;     for (int rr = 0; rr < 16; ++rr) { const int t = 16 * w + rr; const uint4 wv = srow[rr];
;         float x[8] = {bflo(wv.x), bfhi(wv.x), bflo(wv.y), bfhi(wv.y), bflo(wv.z), bfhi(wv.z), bflo(wv.w), bfhi(wv.w)};
;         float s = 0.f;
; #pragma unroll
;         for (int i = 0; i < 8; ++i) s += x[i];
;         const float mu = wave_sum(s) * (1.f / 512.f); float s2 = 0.f;
; #pragma unroll
;         for (int i = 0; i < 8; ++i) { const float d = x[i] - mu; s2 += d * d; }
;         const float var = wave_sum(s2) * (1.f / 512.f);
;         if (lane == 0) { mean[t] = mu; rstd[t] = rsqrtf(var + EPS); } }
.LBB0_363:
	s_or_b64 exec, exec, s[22:23]
	s_waitcnt vmcnt(20)
	v_lshlrev_b32_e32 v116, 16, v112
	v_and_b32_e32 v117, 0xffff0000, v112
	v_add_f32_e32 v112, 0, v116
	s_waitcnt lgkmcnt(0)
	v_lshlrev_b32_e32 v118, 16, v113
	v_add_f32_e32 v112, v112, v117
	v_and_b32_e32 v113, 0xffff0000, v113
	v_add_f32_e32 v112, v112, v118
	v_lshlrev_b32_e32 v119, 16, v114
	v_add_f32_e32 v112, v112, v113
	v_and_b32_e32 v114, 0xffff0000, v114
	v_add_f32_e32 v112, v112, v119
	v_lshlrev_b32_e32 v120, 16, v115
	v_add_f32_e32 v112, v112, v114
	v_and_b32_e32 v115, 0xffff0000, v115
	v_add_f32_e32 v112, v112, v120
	v_add_f32_e32 v112, v112, v115
	s_waitcnt lgkmcnt(0)
	s_nop 1
	v_add_f32_dpp v112, v112, v112 quad_perm:[1,0,3,2] row_mask:0xf bank_mask:0xf
	s_waitcnt lgkmcnt(0)
	s_nop 1
	v_add_f32_dpp v112, v112, v112 quad_perm:[2,3,0,1] row_mask:0xf bank_mask:0xf
	s_waitcnt lgkmcnt(0)
	s_nop 1
	v_add_f32_dpp v112, v112, v112 row_half_mirror row_mask:0xf bank_mask:0xf
	s_waitcnt lgkmcnt(0)
	s_nop 1
	v_add_f32_dpp v112, v112, v112 row_mirror row_mask:0xf bank_mask:0xf
	s_waitcnt lgkmcnt(0)
	v_mov_b32_e32 v121, v112
	s_nop 1
	v_permlane16_swap_b32_e32 v112, v121
	v_add_f32_e32 v112, v112, v121
	s_waitcnt lgkmcnt(0)
	v_mov_b32_e32 v121, v112
	s_nop 1
	v_permlane32_swap_b32_e32 v112, v121
	v_add_f32_e32 v112, v112, v121
	v_fmac_f32_e32 v117, 0xbb000000, v112
	v_fmac_f32_e32 v116, 0xbb000000, v112
	v_mul_f32_e32 v117, v117, v117
	v_fmac_f32_e32 v118, 0xbb000000, v112
	v_fmac_f32_e32 v117, v116, v116
	v_fmac_f32_e32 v113, 0xbb000000, v112
	v_fmac_f32_e32 v117, v118, v118
	v_fmac_f32_e32 v119, 0xbb000000, v112
	v_fmac_f32_e32 v117, v113, v113
	v_fmac_f32_e32 v114, 0xbb000000, v112
	v_fmac_f32_e32 v117, v119, v119
	v_fmac_f32_e32 v120, 0xbb000000, v112
	v_fmac_f32_e32 v117, v114, v114
	v_fmac_f32_e32 v117, v120, v120
	v_fmac_f32_e32 v115, 0xbb000000, v112
	v_fmac_f32_e32 v117, v115, v115
	s_waitcnt lgkmcnt(0)
	s_nop 1
	v_add_f32_dpp v113, v117, v117 quad_perm:[1,0,3,2] row_mask:0xf bank_mask:0xf
	s_waitcnt lgkmcnt(0)
	s_nop 1
	v_add_f32_dpp v113, v113, v113 quad_perm:[2,3,0,1] row_mask:0xf bank_mask:0xf
	s_waitcnt lgkmcnt(0)
	s_nop 1
	v_add_f32_dpp v113, v113, v113 row_half_mirror row_mask:0xf bank_mask:0xf
	s_waitcnt lgkmcnt(0)
	s_nop 1
	v_add_f32_dpp v113, v113, v113 row_mirror row_mask:0xf bank_mask:0xf
	s_waitcnt lgkmcnt(0)
	v_mov_b32_e32 v114, v113
	s_nop 1
	v_permlane16_swap_b32_e32 v113, v114
	v_add_f32_e32 v113, v113, v114
	v_mov_b32_e32 v114, v113
	s_nop 1
	v_permlane32_swap_b32_e32 v113, v114
	s_and_saveexec_b64 s[22:23], vcc
	s_cbranch_execz .LBB0_365
	s_waitcnt lgkmcnt(0)
	v_add_f32_e32 v113, v113, v114
	v_fmamk_f32 v113, v113, 0x3b000000, v179
	v_mul_f32_e32 v114, 0x4b800000, v113
	v_cmp_gt_f32_e64 s[0:1], s91, v113
	v_mul_f32_e32 v112, 0x3b000000, v112
	s_nop 0
	v_cndmask_b32_e64 v113, v113, v114, s[0:1]
	v_rsq_f32_e32 v113, v113
	v_add_u32_e32 v114, 0x1101c, v166
	ds_write_b32 v114, v112
	v_mul_f32_e32 v112, 0x45800000, v113
	v_cndmask_b32_e64 v112, v113, v112, s[0:1]
	v_add_u32_e32 v113, 0x1121c, v166
	ds_write_b32 v113, v112
.LBB0_365:
	s_or_b64 exec, exec, s[22:23]
	s_waitcnt vmcnt(19)
	v_lshlrev_b32_e32 v112, 16, v108
	v_and_b32_e32 v113, 0xffff0000, v108
	v_add_f32_e32 v108, 0, v112
	s_waitcnt lgkmcnt(0)
	v_lshlrev_b32_e32 v114, 16, v109
	v_add_f32_e32 v108, v108, v113
	v_and_b32_e32 v109, 0xffff0000, v109
	v_add_f32_e32 v108, v108, v114
	v_lshlrev_b32_e32 v115, 16, v110
	v_add_f32_e32 v108, v108, v109
	v_and_b32_e32 v110, 0xffff0000, v110
	v_add_f32_e32 v108, v108, v115
	v_lshlrev_b32_e32 v116, 16, v111
	v_add_f32_e32 v108, v108, v110
	v_and_b32_e32 v111, 0xffff0000, v111
	v_add_f32_e32 v108, v108, v116
	v_add_f32_e32 v108, v108, v111
	s_waitcnt lgkmcnt(0)
	s_nop 1
	v_add_f32_dpp v108, v108, v108 quad_perm:[1,0,3,2] row_mask:0xf bank_mask:0xf
	s_waitcnt lgkmcnt(0)
	s_nop 1
	v_add_f32_dpp v108, v108, v108 quad_perm:[2,3,0,1] row_mask:0xf bank_mask:0xf
	s_waitcnt lgkmcnt(0)
	s_nop 1
	v_add_f32_dpp v108, v108, v108 row_half_mirror row_mask:0xf bank_mask:0xf
	s_waitcnt lgkmcnt(0)
	s_nop 1
	v_add_f32_dpp v108, v108, v108 row_mirror row_mask:0xf bank_mask:0xf
	s_waitcnt lgkmcnt(0)
	v_mov_b32_e32 v117, v108
	s_nop 1
	v_permlane16_swap_b32_e32 v108, v117
	v_add_f32_e32 v108, v108, v117
	s_waitcnt lgkmcnt(0)
	v_mov_b32_e32 v117, v108
	s_nop 1
	v_permlane32_swap_b32_e32 v108, v117
	v_add_f32_e32 v108, v108, v117
	v_fmac_f32_e32 v113, 0xbb000000, v108
	v_fmac_f32_e32 v112, 0xbb000000, v108
	v_mul_f32_e32 v113, v113, v113
	v_fmac_f32_e32 v114, 0xbb000000, v108
	v_fmac_f32_e32 v113, v112, v112
	v_fmac_f32_e32 v109, 0xbb000000, v108
	v_fmac_f32_e32 v113, v114, v114
	v_fmac_f32_e32 v115, 0xbb000000, v108
	v_fmac_f32_e32 v113, v109, v109
	v_fmac_f32_e32 v110, 0xbb000000, v108
	v_fmac_f32_e32 v113, v115, v115
	v_fmac_f32_e32 v116, 0xbb000000, v108
	v_fmac_f32_e32 v113, v110, v110
	v_fmac_f32_e32 v113, v116, v116
	v_fmac_f32_e32 v111, 0xbb000000, v108
	v_fmac_f32_e32 v113, v111, v111
	s_waitcnt lgkmcnt(0)
	s_nop 1
	v_add_f32_dpp v109, v113, v113 quad_perm:[1,0,3,2] row_mask:0xf bank_mask:0xf
	s_waitcnt lgkmcnt(0)
	s_nop 1
	v_add_f32_dpp v109, v109, v109 quad_perm:[2,3,0,1] row_mask:0xf bank_mask:0xf
	s_waitcnt lgkmcnt(0)
	s_nop 1
	v_add_f32_dpp v109, v109, v109 row_half_mirror row_mask:0xf bank_mask:0xf
	s_waitcnt lgkmcnt(0)
	s_nop 1
	v_add_f32_dpp v109, v109, v109 row_mirror row_mask:0xf bank_mask:0xf
	s_waitcnt lgkmcnt(0)
	v_mov_b32_e32 v110, v109
	s_nop 1
	v_permlane16_swap_b32_e32 v109, v110
	v_add_f32_e32 v109, v109, v110
	v_mov_b32_e32 v110, v109
	s_nop 1
	v_permlane32_swap_b32_e32 v109, v110
	s_and_saveexec_b64 s[22:23], vcc
	s_cbranch_execz .LBB0_367
	s_waitcnt lgkmcnt(0)
	v_add_f32_e32 v109, v109, v110
	v_fmamk_f32 v109, v109, 0x3b000000, v179
	v_mul_f32_e32 v110, 0x4b800000, v109
	v_cmp_gt_f32_e64 s[0:1], s91, v109
	v_mul_f32_e32 v108, 0x3b000000, v108
	s_nop 0
	v_cndmask_b32_e64 v109, v109, v110, s[0:1]
	v_rsq_f32_e32 v109, v109
	v_add_u32_e32 v110, 0x11020, v166
	ds_write_b32 v110, v108
	v_mul_f32_e32 v108, 0x45800000, v109
	v_cndmask_b32_e64 v108, v109, v108, s[0:1]
	v_add_u32_e32 v109, 0x11220, v166
	ds_write_b32 v109, v108
; __device__ __forceinline__ float bflo(unsigned w) { return __uint_as_float(w << 16); }
; __device__ __forceinline__ float bfhi(unsigned w) { return __uint_as_float(w & 0xffff0000u); }
; __device__ __forceinline__ float wave_sum(float v) {
; #pragma unroll
;     for (int o = 1; o < 64; o <<= 1) v += __shfl_xor(v, o);
;     return v;
; }
; __device__ __forceinline__ void gmlp_item(const u16* P, const float* lnw, const float* lnb, const float* wsl  , const float* bsl  , u16* Y, int c, int h, LAS unsigned char* L, int tid) {
;     ...
;     for (int rr = 0; rr < 16; ++rr) { const int t = 16 * w + rr; const uint4 wv = srow[rr];
;         float x[8] = {bflo(wv.x), bfhi(wv.x), bflo(wv.y), bfhi(wv.y), bflo(wv.z), bfhi(wv.z), bflo(wv.w), bfhi(wv.w)};
;         float s = 0.f;
; #pragma unroll
;         for (int i = 0; i < 8; ++i) s += x[i];
;         const float mu = wave_sum(s) * (1.f / 512.f); float s2 = 0.f;
; #pragma unroll
;         for (int i = 0; i < 8; ++i) { const float d = x[i] - mu; s2 += d * d; }
;         const float var = wave_sum(s2) * (1.f / 512.f);
;         if (lane == 0) { mean[t] = mu; rstd[t] = rsqrtf(var + EPS); } }
.LBB0_367:
	s_or_b64 exec, exec, s[22:23]
	s_waitcnt vmcnt(18)
	v_lshlrev_b32_e32 v108, 16, v104
	v_and_b32_e32 v109, 0xffff0000, v104
	v_add_f32_e32 v104, 0, v108
	s_waitcnt lgkmcnt(0)
	v_lshlrev_b32_e32 v110, 16, v105
	v_add_f32_e32 v104, v104, v109
	v_and_b32_e32 v105, 0xffff0000, v105
	v_add_f32_e32 v104, v104, v110
	v_lshlrev_b32_e32 v111, 16, v106
	v_add_f32_e32 v104, v104, v105
	v_and_b32_e32 v106, 0xffff0000, v106
	v_add_f32_e32 v104, v104, v111
	v_lshlrev_b32_e32 v112, 16, v107
	v_add_f32_e32 v104, v104, v106
	v_and_b32_e32 v107, 0xffff0000, v107
	v_add_f32_e32 v104, v104, v112
	v_add_f32_e32 v104, v104, v107
	s_waitcnt lgkmcnt(0)
	s_nop 1
	v_add_f32_dpp v104, v104, v104 quad_perm:[1,0,3,2] row_mask:0xf bank_mask:0xf
	s_waitcnt lgkmcnt(0)
	s_nop 1
	v_add_f32_dpp v104, v104, v104 quad_perm:[2,3,0,1] row_mask:0xf bank_mask:0xf
	s_waitcnt lgkmcnt(0)
	s_nop 1
	v_add_f32_dpp v104, v104, v104 row_half_mirror row_mask:0xf bank_mask:0xf
	s_waitcnt lgkmcnt(0)
	s_nop 1
	v_add_f32_dpp v104, v104, v104 row_mirror row_mask:0xf bank_mask:0xf
	s_waitcnt lgkmcnt(0)
	v_mov_b32_e32 v113, v104
	s_nop 1
	v_permlane16_swap_b32_e32 v104, v113
	v_add_f32_e32 v104, v104, v113
	s_waitcnt lgkmcnt(0)
	v_mov_b32_e32 v113, v104
	s_nop 1
	v_permlane32_swap_b32_e32 v104, v113
	v_add_f32_e32 v104, v104, v113
	v_fmac_f32_e32 v109, 0xbb000000, v104
	v_fmac_f32_e32 v108, 0xbb000000, v104
	v_mul_f32_e32 v109, v109, v109
	v_fmac_f32_e32 v110, 0xbb000000, v104
	v_fmac_f32_e32 v109, v108, v108
	v_fmac_f32_e32 v105, 0xbb000000, v104
	v_fmac_f32_e32 v109, v110, v110
	v_fmac_f32_e32 v111, 0xbb000000, v104
	v_fmac_f32_e32 v109, v105, v105
	v_fmac_f32_e32 v106, 0xbb000000, v104
	v_fmac_f32_e32 v109, v111, v111
	v_fmac_f32_e32 v112, 0xbb000000, v104
	v_fmac_f32_e32 v109, v106, v106
	v_fmac_f32_e32 v109, v112, v112
	v_fmac_f32_e32 v107, 0xbb000000, v104
	v_fmac_f32_e32 v109, v107, v107
	s_waitcnt lgkmcnt(0)
	s_nop 1
	v_add_f32_dpp v105, v109, v109 quad_perm:[1,0,3,2] row_mask:0xf bank_mask:0xf
	s_waitcnt lgkmcnt(0)
	s_nop 1
	v_add_f32_dpp v105, v105, v105 quad_perm:[2,3,0,1] row_mask:0xf bank_mask:0xf
	s_waitcnt lgkmcnt(0)
	s_nop 1
	v_add_f32_dpp v105, v105, v105 row_half_mirror row_mask:0xf bank_mask:0xf
	s_waitcnt lgkmcnt(0)
	s_nop 1
	v_add_f32_dpp v105, v105, v105 row_mirror row_mask:0xf bank_mask:0xf
	s_waitcnt lgkmcnt(0)
	v_mov_b32_e32 v106, v105
	s_nop 1
	v_permlane16_swap_b32_e32 v105, v106
	v_add_f32_e32 v105, v105, v106
	v_mov_b32_e32 v106, v105
	s_nop 1
	v_permlane32_swap_b32_e32 v105, v106
	s_and_saveexec_b64 s[22:23], vcc
	s_cbranch_execz .LBB0_369
	s_waitcnt lgkmcnt(0)
	v_add_f32_e32 v105, v105, v106
	v_fmamk_f32 v105, v105, 0x3b000000, v179
	v_mul_f32_e32 v106, 0x4b800000, v105
	v_cmp_gt_f32_e64 s[0:1], s91, v105
	v_mul_f32_e32 v104, 0x3b000000, v104
	s_nop 0
	v_cndmask_b32_e64 v105, v105, v106, s[0:1]
	v_rsq_f32_e32 v105, v105
	v_add_u32_e32 v106, 0x11024, v166
	ds_write_b32 v106, v104
	v_mul_f32_e32 v104, 0x45800000, v105
	v_cndmask_b32_e64 v104, v105, v104, s[0:1]
	v_add_u32_e32 v105, 0x11224, v166
	ds_write_b32 v105, v104
.LBB0_369:
	s_or_b64 exec, exec, s[22:23]
	s_waitcnt vmcnt(17)
	v_lshlrev_b32_e32 v104, 16, v100
	v_and_b32_e32 v105, 0xffff0000, v100
	v_add_f32_e32 v100, 0, v104
	s_waitcnt lgkmcnt(0)
	v_lshlrev_b32_e32 v106, 16, v101
	v_add_f32_e32 v100, v100, v105
	v_and_b32_e32 v101, 0xffff0000, v101
	v_add_f32_e32 v100, v100, v106
	v_lshlrev_b32_e32 v107, 16, v102
	v_add_f32_e32 v100, v100, v101
	v_and_b32_e32 v102, 0xffff0000, v102
	v_add_f32_e32 v100, v100, v107
	v_lshlrev_b32_e32 v108, 16, v103
	v_add_f32_e32 v100, v100, v102
	v_and_b32_e32 v103, 0xffff0000, v103
	v_add_f32_e32 v100, v100, v108
	v_add_f32_e32 v100, v100, v103
	s_waitcnt lgkmcnt(0)
	s_nop 1
	v_add_f32_dpp v100, v100, v100 quad_perm:[1,0,3,2] row_mask:0xf bank_mask:0xf
	s_waitcnt lgkmcnt(0)
	s_nop 1
	v_add_f32_dpp v100, v100, v100 quad_perm:[2,3,0,1] row_mask:0xf bank_mask:0xf
	s_waitcnt lgkmcnt(0)
	s_nop 1
	v_add_f32_dpp v100, v100, v100 row_half_mirror row_mask:0xf bank_mask:0xf
	s_waitcnt lgkmcnt(0)
	s_nop 1
	v_add_f32_dpp v100, v100, v100 row_mirror row_mask:0xf bank_mask:0xf
	s_waitcnt lgkmcnt(0)
	v_mov_b32_e32 v109, v100
	s_nop 1
	v_permlane16_swap_b32_e32 v100, v109
	v_add_f32_e32 v100, v100, v109
	s_waitcnt lgkmcnt(0)
	v_mov_b32_e32 v109, v100
	s_nop 1
	v_permlane32_swap_b32_e32 v100, v109
	v_add_f32_e32 v100, v100, v109
	v_fmac_f32_e32 v105, 0xbb000000, v100
	v_fmac_f32_e32 v104, 0xbb000000, v100
	v_mul_f32_e32 v105, v105, v105
	v_fmac_f32_e32 v106, 0xbb000000, v100
	v_fmac_f32_e32 v105, v104, v104
	v_fmac_f32_e32 v101, 0xbb000000, v100
	v_fmac_f32_e32 v105, v106, v106
	v_fmac_f32_e32 v107, 0xbb000000, v100
	v_fmac_f32_e32 v105, v101, v101
	v_fmac_f32_e32 v102, 0xbb000000, v100
	v_fmac_f32_e32 v105, v107, v107
	v_fmac_f32_e32 v108, 0xbb000000, v100
	v_fmac_f32_e32 v105, v102, v102
	v_fmac_f32_e32 v105, v108, v108
	v_fmac_f32_e32 v103, 0xbb000000, v100
	v_fmac_f32_e32 v105, v103, v103
	s_waitcnt lgkmcnt(0)
	s_nop 1
	v_add_f32_dpp v101, v105, v105 quad_perm:[1,0,3,2] row_mask:0xf bank_mask:0xf
	s_waitcnt lgkmcnt(0)
	s_nop 1
	v_add_f32_dpp v101, v101, v101 quad_perm:[2,3,0,1] row_mask:0xf bank_mask:0xf
	s_waitcnt lgkmcnt(0)
	s_nop 1
	v_add_f32_dpp v101, v101, v101 row_half_mirror row_mask:0xf bank_mask:0xf
	s_waitcnt lgkmcnt(0)
	s_nop 1
	v_add_f32_dpp v101, v101, v101 row_mirror row_mask:0xf bank_mask:0xf
	s_waitcnt lgkmcnt(0)
	v_mov_b32_e32 v102, v101
	s_nop 1
	v_permlane16_swap_b32_e32 v101, v102
	v_add_f32_e32 v101, v101, v102
	v_mov_b32_e32 v102, v101
	s_nop 1
	v_permlane32_swap_b32_e32 v101, v102
	s_and_saveexec_b64 s[22:23], vcc
	s_cbranch_execz .LBB0_371
	s_waitcnt lgkmcnt(0)
	v_add_f32_e32 v101, v101, v102
	v_fmamk_f32 v101, v101, 0x3b000000, v179
	v_mul_f32_e32 v102, 0x4b800000, v101
	v_cmp_gt_f32_e64 s[0:1], s91, v101
	v_mul_f32_e32 v100, 0x3b000000, v100
	s_nop 0
	v_cndmask_b32_e64 v101, v101, v102, s[0:1]
	v_rsq_f32_e32 v101, v101
	v_add_u32_e32 v102, 0x11028, v166
	ds_write_b32 v102, v100
	v_mul_f32_e32 v100, 0x45800000, v101
	v_cndmask_b32_e64 v100, v101, v100, s[0:1]
	v_add_u32_e32 v101, 0x11228, v166
	ds_write_b32 v101, v100
; __device__ __forceinline__ float bflo(unsigned w) { return __uint_as_float(w << 16); }
; __device__ __forceinline__ float bfhi(unsigned w) { return __uint_as_float(w & 0xffff0000u); }
; __device__ __forceinline__ float wave_sum(float v) {
; #pragma unroll
;     for (int o = 1; o < 64; o <<= 1) v += __shfl_xor(v, o);
;     return v;
; }
; __device__ __forceinline__ void gmlp_item(const u16* P, const float* lnw, const float* lnb, const float* wsl  , const float* bsl  , u16* Y, int c, int h, LAS unsigned char* L, int tid) {
;     ...
;     for (int rr = 0; rr < 16; ++rr) { const int t = 16 * w + rr; const uint4 wv = srow[rr];
;         float x[8] = {bflo(wv.x), bfhi(wv.x), bflo(wv.y), bfhi(wv.y), bflo(wv.z), bfhi(wv.z), bflo(wv.w), bfhi(wv.w)};
;         float s = 0.f;
; #pragma unroll
;         for (int i = 0; i < 8; ++i) s += x[i];
;         const float mu = wave_sum(s) * (1.f / 512.f); float s2 = 0.f;
; #pragma unroll
;         for (int i = 0; i < 8; ++i) { const float d = x[i] - mu; s2 += d * d; }
;         const float var = wave_sum(s2) * (1.f / 512.f);
;         if (lane == 0) { mean[t] = mu; rstd[t] = rsqrtf(var + EPS); } }
.LBB0_371:
	s_or_b64 exec, exec, s[22:23]
	s_waitcnt vmcnt(16)
	v_lshlrev_b32_e32 v100, 16, v96
	v_and_b32_e32 v101, 0xffff0000, v96
	v_add_f32_e32 v96, 0, v100
	s_waitcnt lgkmcnt(0)
	v_lshlrev_b32_e32 v102, 16, v97
	v_add_f32_e32 v96, v96, v101
	v_and_b32_e32 v97, 0xffff0000, v97
	v_add_f32_e32 v96, v96, v102
	v_lshlrev_b32_e32 v103, 16, v98
	v_add_f32_e32 v96, v96, v97
	v_and_b32_e32 v98, 0xffff0000, v98
	v_add_f32_e32 v96, v96, v103
	v_lshlrev_b32_e32 v104, 16, v99
	v_add_f32_e32 v96, v96, v98
	v_and_b32_e32 v99, 0xffff0000, v99
	v_add_f32_e32 v96, v96, v104
	v_add_f32_e32 v96, v96, v99
	s_waitcnt lgkmcnt(0)
	s_nop 1
	v_add_f32_dpp v96, v96, v96 quad_perm:[1,0,3,2] row_mask:0xf bank_mask:0xf
	s_waitcnt lgkmcnt(0)
	s_nop 1
	v_add_f32_dpp v96, v96, v96 quad_perm:[2,3,0,1] row_mask:0xf bank_mask:0xf
	s_waitcnt lgkmcnt(0)
	s_nop 1
	v_add_f32_dpp v96, v96, v96 row_half_mirror row_mask:0xf bank_mask:0xf
	s_waitcnt lgkmcnt(0)
	s_nop 1
	v_add_f32_dpp v96, v96, v96 row_mirror row_mask:0xf bank_mask:0xf
	s_waitcnt lgkmcnt(0)
	v_mov_b32_e32 v105, v96
	s_nop 1
	v_permlane16_swap_b32_e32 v96, v105
	v_add_f32_e32 v96, v96, v105
	s_waitcnt lgkmcnt(0)
	v_mov_b32_e32 v105, v96
	s_nop 1
	v_permlane32_swap_b32_e32 v96, v105
	v_add_f32_e32 v96, v96, v105
	v_fmac_f32_e32 v101, 0xbb000000, v96
	v_fmac_f32_e32 v100, 0xbb000000, v96
	v_mul_f32_e32 v101, v101, v101
	v_fmac_f32_e32 v102, 0xbb000000, v96
	v_fmac_f32_e32 v101, v100, v100
	v_fmac_f32_e32 v97, 0xbb000000, v96
	v_fmac_f32_e32 v101, v102, v102
	v_fmac_f32_e32 v103, 0xbb000000, v96
	v_fmac_f32_e32 v101, v97, v97
	v_fmac_f32_e32 v98, 0xbb000000, v96
	v_fmac_f32_e32 v101, v103, v103
	v_fmac_f32_e32 v104, 0xbb000000, v96
	v_fmac_f32_e32 v101, v98, v98
	v_fmac_f32_e32 v101, v104, v104
	v_fmac_f32_e32 v99, 0xbb000000, v96
	v_fmac_f32_e32 v101, v99, v99
	s_waitcnt lgkmcnt(0)
	s_nop 1
	v_add_f32_dpp v97, v101, v101 quad_perm:[1,0,3,2] row_mask:0xf bank_mask:0xf
	s_waitcnt lgkmcnt(0)
	s_nop 1
	v_add_f32_dpp v97, v97, v97 quad_perm:[2,3,0,1] row_mask:0xf bank_mask:0xf
	s_waitcnt lgkmcnt(0)
	s_nop 1
	v_add_f32_dpp v97, v97, v97 row_half_mirror row_mask:0xf bank_mask:0xf
	s_waitcnt lgkmcnt(0)
	s_nop 1
	v_add_f32_dpp v97, v97, v97 row_mirror row_mask:0xf bank_mask:0xf
	s_waitcnt lgkmcnt(0)
	v_mov_b32_e32 v98, v97
	s_nop 1
	v_permlane16_swap_b32_e32 v97, v98
	v_add_f32_e32 v97, v97, v98
	v_mov_b32_e32 v98, v97
	s_nop 1
	v_permlane32_swap_b32_e32 v97, v98
	s_and_saveexec_b64 s[22:23], vcc
	s_cbranch_execz .LBB0_373
	s_waitcnt lgkmcnt(0)
	v_add_f32_e32 v97, v97, v98
	v_fmamk_f32 v97, v97, 0x3b000000, v179
	v_mul_f32_e32 v98, 0x4b800000, v97
	v_cmp_gt_f32_e64 s[0:1], s91, v97
	v_mul_f32_e32 v96, 0x3b000000, v96
	s_nop 0
	v_cndmask_b32_e64 v97, v97, v98, s[0:1]
	v_rsq_f32_e32 v97, v97
	v_add_u32_e32 v98, 0x1102c, v166
	ds_write_b32 v98, v96
	v_mul_f32_e32 v96, 0x45800000, v97
	v_cndmask_b32_e64 v96, v97, v96, s[0:1]
	v_add_u32_e32 v97, 0x1122c, v166
	ds_write_b32 v97, v96
.LBB0_373:
	s_or_b64 exec, exec, s[22:23]
	s_waitcnt vmcnt(15)
	v_lshlrev_b32_e32 v96, 16, v92
	v_and_b32_e32 v97, 0xffff0000, v92
	v_add_f32_e32 v92, 0, v96
	s_waitcnt lgkmcnt(0)
	v_lshlrev_b32_e32 v98, 16, v93
	v_add_f32_e32 v92, v92, v97
	v_and_b32_e32 v93, 0xffff0000, v93
	v_add_f32_e32 v92, v92, v98
	v_lshlrev_b32_e32 v99, 16, v94
	v_add_f32_e32 v92, v92, v93
	v_and_b32_e32 v94, 0xffff0000, v94
	v_add_f32_e32 v92, v92, v99
	v_lshlrev_b32_e32 v100, 16, v95
	v_add_f32_e32 v92, v92, v94
	v_and_b32_e32 v95, 0xffff0000, v95
	v_add_f32_e32 v92, v92, v100
	v_add_f32_e32 v92, v92, v95
	s_waitcnt lgkmcnt(0)
	s_nop 1
	v_add_f32_dpp v92, v92, v92 quad_perm:[1,0,3,2] row_mask:0xf bank_mask:0xf
	s_waitcnt lgkmcnt(0)
	s_nop 1
	v_add_f32_dpp v92, v92, v92 quad_perm:[2,3,0,1] row_mask:0xf bank_mask:0xf
	s_waitcnt lgkmcnt(0)
	s_nop 1
	v_add_f32_dpp v92, v92, v92 row_half_mirror row_mask:0xf bank_mask:0xf
	s_waitcnt lgkmcnt(0)
	s_nop 1
	v_add_f32_dpp v92, v92, v92 row_mirror row_mask:0xf bank_mask:0xf
	s_waitcnt lgkmcnt(0)
	v_mov_b32_e32 v101, v92
	s_nop 1
	v_permlane16_swap_b32_e32 v92, v101
	v_add_f32_e32 v92, v92, v101
	s_waitcnt lgkmcnt(0)
	v_mov_b32_e32 v101, v92
	s_nop 1
	v_permlane32_swap_b32_e32 v92, v101
	v_add_f32_e32 v92, v92, v101
	v_fmac_f32_e32 v97, 0xbb000000, v92
	v_fmac_f32_e32 v96, 0xbb000000, v92
	v_mul_f32_e32 v97, v97, v97
	v_fmac_f32_e32 v98, 0xbb000000, v92
	v_fmac_f32_e32 v97, v96, v96
	v_fmac_f32_e32 v93, 0xbb000000, v92
	v_fmac_f32_e32 v97, v98, v98
	v_fmac_f32_e32 v99, 0xbb000000, v92
	v_fmac_f32_e32 v97, v93, v93
	v_fmac_f32_e32 v94, 0xbb000000, v92
	v_fmac_f32_e32 v97, v99, v99
	v_fmac_f32_e32 v100, 0xbb000000, v92
	v_fmac_f32_e32 v97, v94, v94
	v_fmac_f32_e32 v97, v100, v100
	v_fmac_f32_e32 v95, 0xbb000000, v92
	v_fmac_f32_e32 v97, v95, v95
	s_waitcnt lgkmcnt(0)
	s_nop 1
	v_add_f32_dpp v93, v97, v97 quad_perm:[1,0,3,2] row_mask:0xf bank_mask:0xf
	s_waitcnt lgkmcnt(0)
	s_nop 1
	v_add_f32_dpp v93, v93, v93 quad_perm:[2,3,0,1] row_mask:0xf bank_mask:0xf
	s_waitcnt lgkmcnt(0)
	s_nop 1
	v_add_f32_dpp v93, v93, v93 row_half_mirror row_mask:0xf bank_mask:0xf
	s_waitcnt lgkmcnt(0)
	s_nop 1
	v_add_f32_dpp v93, v93, v93 row_mirror row_mask:0xf bank_mask:0xf
	s_waitcnt lgkmcnt(0)
	v_mov_b32_e32 v94, v93
	s_nop 1
	v_permlane16_swap_b32_e32 v93, v94
	v_add_f32_e32 v93, v93, v94
	v_mov_b32_e32 v94, v93
	s_nop 1
	v_permlane32_swap_b32_e32 v93, v94
	s_and_saveexec_b64 s[22:23], vcc
	s_cbranch_execz .LBB0_375
	s_waitcnt lgkmcnt(0)
	v_add_f32_e32 v93, v93, v94
	v_fmamk_f32 v93, v93, 0x3b000000, v179
	v_mul_f32_e32 v94, 0x4b800000, v93
	v_cmp_gt_f32_e64 s[0:1], s91, v93
	v_mul_f32_e32 v92, 0x3b000000, v92
	s_nop 0
	v_cndmask_b32_e64 v93, v93, v94, s[0:1]
	v_rsq_f32_e32 v93, v93
	v_add_u32_e32 v94, 0x11030, v166
	ds_write_b32 v94, v92
	v_mul_f32_e32 v92, 0x45800000, v93
	v_cndmask_b32_e64 v92, v93, v92, s[0:1]
	v_add_u32_e32 v93, 0x11230, v166
	ds_write_b32 v93, v92
; __device__ __forceinline__ float bflo(unsigned w) { return __uint_as_float(w << 16); }
; __device__ __forceinline__ float bfhi(unsigned w) { return __uint_as_float(w & 0xffff0000u); }
; __device__ __forceinline__ float wave_sum(float v) {
; #pragma unroll
;     for (int o = 1; o < 64; o <<= 1) v += __shfl_xor(v, o);
;     return v;
; }
; __device__ __forceinline__ void gmlp_item(const u16* P, const float* lnw, const float* lnb, const float* wsl  , const float* bsl  , u16* Y, int c, int h, LAS unsigned char* L, int tid) {
;     ...
;     for (int rr = 0; rr < 16; ++rr) { const int t = 16 * w + rr; const uint4 wv = srow[rr];
;         float x[8] = {bflo(wv.x), bfhi(wv.x), bflo(wv.y), bfhi(wv.y), bflo(wv.z), bfhi(wv.z), bflo(wv.w), bfhi(wv.w)};
;         float s = 0.f;
; #pragma unroll
;         for (int i = 0; i < 8; ++i) s += x[i];
;         const float mu = wave_sum(s) * (1.f / 512.f); float s2 = 0.f;
; #pragma unroll
;         for (int i = 0; i < 8; ++i) { const float d = x[i] - mu; s2 += d * d; }
;         const float var = wave_sum(s2) * (1.f / 512.f);
;         if (lane == 0) { mean[t] = mu; rstd[t] = rsqrtf(var + EPS); } }
.LBB0_375:
	s_or_b64 exec, exec, s[22:23]
	s_waitcnt vmcnt(14)
	v_lshlrev_b32_e32 v92, 16, v88
	v_and_b32_e32 v93, 0xffff0000, v88
	v_add_f32_e32 v88, 0, v92
	s_waitcnt lgkmcnt(0)
	v_lshlrev_b32_e32 v94, 16, v89
	v_add_f32_e32 v88, v88, v93
	v_and_b32_e32 v89, 0xffff0000, v89
	v_add_f32_e32 v88, v88, v94
	v_lshlrev_b32_e32 v95, 16, v90
	v_add_f32_e32 v88, v88, v89
	v_and_b32_e32 v90, 0xffff0000, v90
	v_add_f32_e32 v88, v88, v95
	v_lshlrev_b32_e32 v96, 16, v91
	v_add_f32_e32 v88, v88, v90
	v_and_b32_e32 v91, 0xffff0000, v91
	v_add_f32_e32 v88, v88, v96
	v_add_f32_e32 v88, v88, v91
	s_waitcnt lgkmcnt(0)
	s_nop 1
	v_add_f32_dpp v88, v88, v88 quad_perm:[1,0,3,2] row_mask:0xf bank_mask:0xf
	s_waitcnt lgkmcnt(0)
	s_nop 1
	v_add_f32_dpp v88, v88, v88 quad_perm:[2,3,0,1] row_mask:0xf bank_mask:0xf
	s_waitcnt lgkmcnt(0)
	s_nop 1
	v_add_f32_dpp v88, v88, v88 row_half_mirror row_mask:0xf bank_mask:0xf
	s_waitcnt lgkmcnt(0)
	s_nop 1
	v_add_f32_dpp v88, v88, v88 row_mirror row_mask:0xf bank_mask:0xf
	s_waitcnt lgkmcnt(0)
	v_mov_b32_e32 v97, v88
	s_nop 1
	v_permlane16_swap_b32_e32 v88, v97
	v_add_f32_e32 v88, v88, v97
	s_waitcnt lgkmcnt(0)
	v_mov_b32_e32 v97, v88
	s_nop 1
	v_permlane32_swap_b32_e32 v88, v97
	v_add_f32_e32 v88, v88, v97
	v_fmac_f32_e32 v93, 0xbb000000, v88
	v_fmac_f32_e32 v92, 0xbb000000, v88
	v_mul_f32_e32 v93, v93, v93
	v_fmac_f32_e32 v94, 0xbb000000, v88
	v_fmac_f32_e32 v93, v92, v92
	v_fmac_f32_e32 v89, 0xbb000000, v88
	v_fmac_f32_e32 v93, v94, v94
	v_fmac_f32_e32 v95, 0xbb000000, v88
	v_fmac_f32_e32 v93, v89, v89
	v_fmac_f32_e32 v90, 0xbb000000, v88
	v_fmac_f32_e32 v93, v95, v95
	v_fmac_f32_e32 v96, 0xbb000000, v88
	v_fmac_f32_e32 v93, v90, v90
	v_fmac_f32_e32 v93, v96, v96
	v_fmac_f32_e32 v91, 0xbb000000, v88
	v_fmac_f32_e32 v93, v91, v91
	s_waitcnt lgkmcnt(0)
	s_nop 1
	v_add_f32_dpp v89, v93, v93 quad_perm:[1,0,3,2] row_mask:0xf bank_mask:0xf
	s_waitcnt lgkmcnt(0)
	s_nop 1
	v_add_f32_dpp v89, v89, v89 quad_perm:[2,3,0,1] row_mask:0xf bank_mask:0xf
	s_waitcnt lgkmcnt(0)
	s_nop 1
	v_add_f32_dpp v89, v89, v89 row_half_mirror row_mask:0xf bank_mask:0xf
	s_waitcnt lgkmcnt(0)
	s_nop 1
	v_add_f32_dpp v89, v89, v89 row_mirror row_mask:0xf bank_mask:0xf
	s_waitcnt lgkmcnt(0)
	v_mov_b32_e32 v90, v89
	s_nop 1
	v_permlane16_swap_b32_e32 v89, v90
	v_add_f32_e32 v89, v89, v90
	v_mov_b32_e32 v90, v89
	s_nop 1
	v_permlane32_swap_b32_e32 v89, v90
	s_and_saveexec_b64 s[22:23], vcc
	s_cbranch_execz .LBB0_377
	s_waitcnt lgkmcnt(0)
	v_add_f32_e32 v89, v89, v90
	v_fmamk_f32 v89, v89, 0x3b000000, v179
	v_mul_f32_e32 v90, 0x4b800000, v89
	v_cmp_gt_f32_e64 s[0:1], s91, v89
	v_mul_f32_e32 v88, 0x3b000000, v88
	s_nop 0
	v_cndmask_b32_e64 v89, v89, v90, s[0:1]
	v_rsq_f32_e32 v89, v89
	v_add_u32_e32 v90, 0x11034, v166
	ds_write_b32 v90, v88
	v_mul_f32_e32 v88, 0x45800000, v89
	v_cndmask_b32_e64 v88, v89, v88, s[0:1]
	v_add_u32_e32 v89, 0x11234, v166
	ds_write_b32 v89, v88
.LBB0_377:
	s_or_b64 exec, exec, s[22:23]
	s_waitcnt vmcnt(13)
	v_lshlrev_b32_e32 v88, 16, v84
	v_and_b32_e32 v89, 0xffff0000, v84
	v_add_f32_e32 v84, 0, v88
	s_waitcnt lgkmcnt(0)
	v_lshlrev_b32_e32 v90, 16, v85
	v_add_f32_e32 v84, v84, v89
	v_and_b32_e32 v85, 0xffff0000, v85
	v_add_f32_e32 v84, v84, v90
	v_lshlrev_b32_e32 v91, 16, v86
	v_add_f32_e32 v84, v84, v85
	v_and_b32_e32 v86, 0xffff0000, v86
	v_add_f32_e32 v84, v84, v91
	v_lshlrev_b32_e32 v92, 16, v87
	v_add_f32_e32 v84, v84, v86
	v_and_b32_e32 v87, 0xffff0000, v87
	v_add_f32_e32 v84, v84, v92
	v_add_f32_e32 v84, v84, v87
	s_waitcnt lgkmcnt(0)
	s_nop 1
	v_add_f32_dpp v84, v84, v84 quad_perm:[1,0,3,2] row_mask:0xf bank_mask:0xf
	s_waitcnt lgkmcnt(0)
	s_nop 1
	v_add_f32_dpp v84, v84, v84 quad_perm:[2,3,0,1] row_mask:0xf bank_mask:0xf
	s_waitcnt lgkmcnt(0)
	s_nop 1
	v_add_f32_dpp v84, v84, v84 row_half_mirror row_mask:0xf bank_mask:0xf
	s_waitcnt lgkmcnt(0)
	s_nop 1
	v_add_f32_dpp v84, v84, v84 row_mirror row_mask:0xf bank_mask:0xf
	s_waitcnt lgkmcnt(0)
	v_mov_b32_e32 v93, v84
	s_nop 1
	v_permlane16_swap_b32_e32 v84, v93
	v_add_f32_e32 v84, v84, v93
	s_waitcnt lgkmcnt(0)
	v_mov_b32_e32 v93, v84
	s_nop 1
	v_permlane32_swap_b32_e32 v84, v93
	v_add_f32_e32 v84, v84, v93
	v_fmac_f32_e32 v89, 0xbb000000, v84
	v_fmac_f32_e32 v88, 0xbb000000, v84
	v_mul_f32_e32 v89, v89, v89
	v_fmac_f32_e32 v90, 0xbb000000, v84
	v_fmac_f32_e32 v89, v88, v88
	v_fmac_f32_e32 v85, 0xbb000000, v84
	v_fmac_f32_e32 v89, v90, v90
	v_fmac_f32_e32 v91, 0xbb000000, v84
	v_fmac_f32_e32 v89, v85, v85
	v_fmac_f32_e32 v86, 0xbb000000, v84
	v_fmac_f32_e32 v89, v91, v91
	v_fmac_f32_e32 v92, 0xbb000000, v84
	v_fmac_f32_e32 v89, v86, v86
	v_fmac_f32_e32 v89, v92, v92
	v_fmac_f32_e32 v87, 0xbb000000, v84
	v_fmac_f32_e32 v89, v87, v87
	s_waitcnt lgkmcnt(0)
	s_nop 1
	v_add_f32_dpp v85, v89, v89 quad_perm:[1,0,3,2] row_mask:0xf bank_mask:0xf
	s_waitcnt lgkmcnt(0)
	s_nop 1
	v_add_f32_dpp v85, v85, v85 quad_perm:[2,3,0,1] row_mask:0xf bank_mask:0xf
	s_waitcnt lgkmcnt(0)
	s_nop 1
	v_add_f32_dpp v85, v85, v85 row_half_mirror row_mask:0xf bank_mask:0xf
	s_waitcnt lgkmcnt(0)
	s_nop 1
	v_add_f32_dpp v85, v85, v85 row_mirror row_mask:0xf bank_mask:0xf
	s_waitcnt lgkmcnt(0)
	v_mov_b32_e32 v86, v85
	s_nop 1
	v_permlane16_swap_b32_e32 v85, v86
	v_add_f32_e32 v85, v85, v86
	v_mov_b32_e32 v86, v85
	s_nop 1
	v_permlane32_swap_b32_e32 v85, v86
	s_and_saveexec_b64 s[22:23], vcc
	s_cbranch_execz .LBB0_379
	s_waitcnt lgkmcnt(0)
	v_add_f32_e32 v85, v85, v86
	v_fmamk_f32 v85, v85, 0x3b000000, v179
	v_mul_f32_e32 v86, 0x4b800000, v85
	v_cmp_gt_f32_e64 s[0:1], s91, v85
	v_mul_f32_e32 v84, 0x3b000000, v84
	s_nop 0
	v_cndmask_b32_e64 v85, v85, v86, s[0:1]
	v_rsq_f32_e32 v85, v85
	v_add_u32_e32 v86, 0x11038, v166
	ds_write_b32 v86, v84
	v_mul_f32_e32 v84, 0x45800000, v85
	v_cndmask_b32_e64 v84, v85, v84, s[0:1]
	v_add_u32_e32 v85, 0x11238, v166
	ds_write_b32 v85, v84
; __device__ __forceinline__ float bflo(unsigned w) { return __uint_as_float(w << 16); }
; __device__ __forceinline__ float bfhi(unsigned w) { return __uint_as_float(w & 0xffff0000u); }
; __device__ __forceinline__ float wave_sum(float v) {
; #pragma unroll
;     for (int o = 1; o < 64; o <<= 1) v += __shfl_xor(v, o);
;     return v;
; }
; __device__ __forceinline__ void gmlp_item(const u16* P, const float* lnw, const float* lnb, const float* wsl  , const float* bsl  , u16* Y, int c, int h, LAS unsigned char* L, int tid) {
;     ...
;     for (int rr = 0; rr < 16; ++rr) { const int t = 16 * w + rr; const uint4 wv = srow[rr];
;         float x[8] = {bflo(wv.x), bfhi(wv.x), bflo(wv.y), bfhi(wv.y), bflo(wv.z), bfhi(wv.z), bflo(wv.w), bfhi(wv.w)};
;         float s = 0.f;
; #pragma unroll
;         for (int i = 0; i < 8; ++i) s += x[i];
;         const float mu = wave_sum(s) * (1.f / 512.f); float s2 = 0.f;
; #pragma unroll
;         for (int i = 0; i < 8; ++i) { const float d = x[i] - mu; s2 += d * d; }
;         const float var = wave_sum(s2) * (1.f / 512.f);
;         if (lane == 0) { mean[t] = mu; rstd[t] = rsqrtf(var + EPS); } }
.LBB0_379:
	s_or_b64 exec, exec, s[22:23]
	s_waitcnt vmcnt(12)
	v_lshlrev_b32_e32 v84, 16, v80
	v_and_b32_e32 v85, 0xffff0000, v80
	v_add_f32_e32 v80, 0, v84
	s_waitcnt lgkmcnt(0)
	v_lshlrev_b32_e32 v86, 16, v81
	v_add_f32_e32 v80, v80, v85
	v_and_b32_e32 v81, 0xffff0000, v81
	v_add_f32_e32 v80, v80, v86
	v_lshlrev_b32_e32 v87, 16, v82
	v_add_f32_e32 v80, v80, v81
	v_and_b32_e32 v82, 0xffff0000, v82
	v_add_f32_e32 v80, v80, v87
	v_lshlrev_b32_e32 v88, 16, v83
	v_add_f32_e32 v80, v80, v82
	v_and_b32_e32 v83, 0xffff0000, v83
	v_add_f32_e32 v80, v80, v88
	v_add_f32_e32 v80, v80, v83
	s_lshl_b32 s18, s18, 7
	s_waitcnt lgkmcnt(0)
	s_nop 1
	v_add_f32_dpp v80, v80, v80 quad_perm:[1,0,3,2] row_mask:0xf bank_mask:0xf
	s_waitcnt lgkmcnt(0)
	s_nop 1
	v_add_f32_dpp v80, v80, v80 quad_perm:[2,3,0,1] row_mask:0xf bank_mask:0xf
	s_waitcnt lgkmcnt(0)
	s_nop 1
	v_add_f32_dpp v80, v80, v80 row_half_mirror row_mask:0xf bank_mask:0xf
	s_waitcnt lgkmcnt(0)
	s_nop 1
	v_add_f32_dpp v80, v80, v80 row_mirror row_mask:0xf bank_mask:0xf
	s_waitcnt lgkmcnt(0)
	v_mov_b32_e32 v89, v80
	s_nop 1
	v_permlane16_swap_b32_e32 v80, v89
	v_add_f32_e32 v80, v80, v89
	s_waitcnt lgkmcnt(0)
	v_mov_b32_e32 v89, v80
	s_nop 1
	v_permlane32_swap_b32_e32 v80, v89
	v_add_f32_e32 v80, v80, v89
	v_fmac_f32_e32 v85, 0xbb000000, v80
	v_fmac_f32_e32 v84, 0xbb000000, v80
	v_mul_f32_e32 v85, v85, v85
	v_fmac_f32_e32 v86, 0xbb000000, v80
	v_fmac_f32_e32 v85, v84, v84
	v_fmac_f32_e32 v81, 0xbb000000, v80
	v_fmac_f32_e32 v85, v86, v86
	v_fmac_f32_e32 v87, 0xbb000000, v80
	v_fmac_f32_e32 v85, v81, v81
	v_fmac_f32_e32 v82, 0xbb000000, v80
	v_fmac_f32_e32 v85, v87, v87
	v_fmac_f32_e32 v88, 0xbb000000, v80
	v_fmac_f32_e32 v85, v82, v82
	v_fmac_f32_e32 v85, v88, v88
	v_fmac_f32_e32 v83, 0xbb000000, v80
	v_fmac_f32_e32 v85, v83, v83
	s_waitcnt lgkmcnt(0)
	s_nop 1
	v_add_f32_dpp v81, v85, v85 quad_perm:[1,0,3,2] row_mask:0xf bank_mask:0xf
	s_waitcnt lgkmcnt(0)
	s_nop 1
	v_add_f32_dpp v81, v81, v81 quad_perm:[2,3,0,1] row_mask:0xf bank_mask:0xf
	s_waitcnt lgkmcnt(0)
	s_nop 1
	v_add_f32_dpp v81, v81, v81 row_half_mirror row_mask:0xf bank_mask:0xf
	s_waitcnt lgkmcnt(0)
	s_nop 1
	v_add_f32_dpp v81, v81, v81 row_mirror row_mask:0xf bank_mask:0xf
	s_waitcnt lgkmcnt(0)
	v_mov_b32_e32 v82, v81
	s_nop 1
	v_permlane16_swap_b32_e32 v81, v82
	v_add_f32_e32 v81, v81, v82
	v_mov_b32_e32 v82, v81
	s_nop 1
	v_permlane32_swap_b32_e32 v81, v82
	s_and_saveexec_b64 s[0:1], vcc
	s_cbranch_execz .LBB0_338
	s_waitcnt lgkmcnt(0)
	v_add_f32_e32 v81, v81, v82
	v_fmamk_f32 v81, v81, 0x3b000000, v179
	v_mul_f32_e32 v82, 0x4b800000, v81
	v_cmp_gt_f32_e32 vcc, s91, v81
	v_mul_f32_e32 v80, 0x3b000000, v80
	s_nop 0
	v_cndmask_b32_e32 v81, v81, v82, vcc
	v_rsq_f32_e32 v81, v81
	v_add_u32_e32 v82, 0x1103c, v166
	ds_write_b32 v82, v80
	v_mul_f32_e32 v80, 0x45800000, v81
	v_cndmask_b32_e32 v80, v81, v80, vcc
	v_add_u32_e32 v81, 0x1123c, v166
	ds_write_b32 v81, v80
	s_branch .LBB0_338
